# S2+peel+XL + sigmoid in-proj epilogue specialised into GA / MA-MB copies (no per-element select)
# speedup vs baseline: 1.0010x; 1.0010x over previous
.LBB0_174:
	s_cmp_gt_i32 s16, 7
	s_mov_b64 s[42:43], -1
	s_cbranch_scc0 .LBB0_196
	s_add_i32 s17, s16, -12
	s_cmp_gt_u32 s17, 15
	s_cbranch_scc0 .LBB0_177
	v_ashrrev_i32_e32 v171, 31, v170
	v_lshlrev_b64 v[134:135], 6, v[170:171]
	v_lshl_add_u64 v[146:147], s[92:93], 0, v[134:135]
	global_load_dwordx4 v[134:137], v[146:147], off offset:32
	global_load_dwordx4 v[138:141], v[146:147], off offset:48
	global_load_dwordx4 v[142:145], v[146:147], off
	s_nop 0
	global_load_dwordx4 v[146:149], v[146:147], off offset:16
	s_cmp_lt_u32 s16, 12
	s_cselect_b64 vcc, -1, 0
	s_cmp_lt_u32 s16, 32
	s_mov_b32 s17, 0x18c00000
	s_cselect_b32 s17, s17, 0x1ac00000
	s_and_b64 s[42:43], vcc, exec
	s_cselect_b32 s17, 0x12c00000, s17
	s_add_u32 s42, s38, s17
	s_addc_u32 s43, s39, 0
	s_add_i32 s17, s16, -8
	s_and_b32 s22, s16, 3
	s_and_b64 s[46:47], vcc, exec
	s_cselect_b32 s17, s17, s22
	v_lshlrev_b32_e32 v0, 1, v222
	v_lshl_or_b32 v0, s17, 9, v0
	v_lshl_add_u64 v[130:131], s[42:43], 0, v[0:1]
	v_lshlrev_b64 v[132:133], 11, v[170:171]
	v_lshl_add_u64 v[132:133], v[130:131], 0, v[132:133]
	s_mov_b64 s[42:43], 0
	s_cbranch_vccz .Lsig_ng
	s_waitcnt vmcnt(0)
	v_pk_add_f32 v[136:137], v[136:137], v[140:141]
	v_pk_add_f32 v[134:135], v[134:135], v[138:139]
	v_pk_add_f32 v[144:145], v[144:145], v[148:149]
	v_pk_add_f32 v[142:143], v[142:143], v[146:147]
	v_pk_add_f32 v[136:137], v[144:145], v[136:137]
	v_pk_add_f32 v[134:135], v[142:143], v[134:135]
	s_nop 0
	v_pk_mov_b32 v[138:139], v[134:135], v[136:137] op_sel:[1,0]
	v_mov_b32_e32 v135, v137
	v_pk_add_f32 v[134:135], v[138:139], v[134:135]
	s_nop 0
	v_add_f32_e32 v0, v134, v135
	v_fmamk_f32 v0, v0, 0x3a800000, v211
	v_rsq_f32_e32 v0, v0
	s_nop 0
	v_pk_mul_f32 v[136:137], v[126:127], v[0:1] op_sel_hi:[1,0]
	v_pk_mul_f32 v[140:141], v[122:123], v[0:1] op_sel_hi:[1,0]
	v_mul_f32_e32 v142, 0xbfb8aa3b, v136
	v_exp_f32_e32 v142, v142
	v_mul_f32_e32 v143, 0xbfb8aa3b, v140
	v_exp_f32_e32 v143, v143
	v_pk_mul_f32 v[134:135], v[128:129], v[0:1] op_sel_hi:[1,0]
	v_add_f32_e32 v142, 1.0, v142
	v_rcp_f32_e32 v142, v142
	v_add_f32_e32 v143, 1.0, v143
	v_rcp_f32_e32 v143, v143
	v_pk_mul_f32 v[138:139], v[124:125], v[0:1] op_sel_hi:[1,0]
	v_mul_f32_e32 v136, v136, v142
	v_mul_f32_e32 v140, v140, v143
	v_mul_f32_e32 v142, 0xbfb8aa3b, v137
	v_exp_f32_e32 v142, v142
	v_mul_f32_e32 v143, 0xbfb8aa3b, v141
	v_exp_f32_e32 v143, v143
	v_add_f32_e32 v142, 1.0, v142
	v_rcp_f32_e32 v142, v142
	v_add_f32_e32 v143, 1.0, v143
	v_rcp_f32_e32 v143, v143
	v_mul_f32_e32 v137, v137, v142
	v_mul_f32_e32 v141, v141, v143
	v_mul_f32_e32 v142, 0xbfb8aa3b, v134
	v_exp_f32_e32 v142, v142
	v_mul_f32_e32 v143, 0xbfb8aa3b, v138
	v_exp_f32_e32 v143, v143
	v_add_f32_e32 v142, 1.0, v142
	v_rcp_f32_e32 v142, v142
	v_add_f32_e32 v143, 1.0, v143
	v_rcp_f32_e32 v143, v143
	v_mul_f32_e32 v142, v134, v142
	v_mul_f32_e32 v138, v138, v143
	v_mul_f32_e32 v134, 0xbfb8aa3b, v135
	v_exp_f32_e32 v134, v134
	v_mul_f32_e32 v143, 0xbfb8aa3b, v139
	v_exp_f32_e32 v143, v143
	v_add_f32_e32 v134, 1.0, v134
	v_rcp_f32_e32 v134, v134
	v_add_f32_e32 v143, 1.0, v143
	v_rcp_f32_e32 v143, v143
	v_mul_f32_e32 v135, v135, v134
	v_mul_f32_e32 v139, v139, v143
	v_cvt_pk_bf16_f32 v134, v136, v137
	v_cvt_pk_bf16_f32 v135, v142, v135
	v_cvt_pk_bf16_f32 v136, v140, v141
	v_cvt_pk_bf16_f32 v137, v138, v139
	v_pk_mul_f32 v[138:139], v[118:119], v[0:1] op_sel_hi:[1,0]
	global_store_dwordx4 v[132:133], v[134:137], off
	v_pk_mul_f32 v[140:141], v[110:111], v[0:1] op_sel_hi:[1,0]
	s_nop 0
	v_pk_mul_f32 v[134:135], v[120:121], v[0:1] op_sel_hi:[1,0]
	v_pk_mul_f32 v[136:137], v[112:113], v[0:1] op_sel_hi:[1,0]
	v_mul_f32_e32 v0, 0xbfb8aa3b, v138
	v_exp_f32_e32 v0, v0
	v_mul_f32_e32 v142, 0xbfb8aa3b, v140
	v_exp_f32_e32 v142, v142
	v_add_f32_e32 v0, 1.0, v0
	v_rcp_f32_e32 v0, v0
	v_add_f32_e32 v142, 1.0, v142
	v_rcp_f32_e32 v142, v142
	v_mul_f32_e32 v0, v138, v0
	v_mul_f32_e32 v138, v140, v142
	v_mul_f32_e32 v140, 0xbfb8aa3b, v139
	v_exp_f32_e32 v140, v140
	v_mul_f32_e32 v142, 0xbfb8aa3b, v141
	v_exp_f32_e32 v142, v142
	v_add_f32_e32 v140, 1.0, v140
	v_rcp_f32_e32 v140, v140
	v_add_f32_e32 v142, 1.0, v142
	v_rcp_f32_e32 v142, v142
	v_mul_f32_e32 v139, v139, v140
	v_mul_f32_e32 v140, v141, v142
	v_mul_f32_e32 v141, 0xbfb8aa3b, v134
	v_exp_f32_e32 v141, v141
	v_mul_f32_e32 v142, 0xbfb8aa3b, v136
	v_exp_f32_e32 v142, v142
	v_add_f32_e32 v141, 1.0, v141
	v_rcp_f32_e32 v141, v141
	v_add_f32_e32 v142, 1.0, v142
	v_rcp_f32_e32 v142, v142
	v_mul_f32_e32 v141, v134, v141
	v_mul_f32_e32 v142, v136, v142
	v_mul_f32_e32 v134, 0xbfb8aa3b, v135
	v_exp_f32_e32 v134, v134
	v_mul_f32_e32 v136, 0xbfb8aa3b, v137
	v_exp_f32_e32 v136, v136
	v_add_f32_e32 v134, 1.0, v134
	v_rcp_f32_e32 v134, v134
	v_add_f32_e32 v136, 1.0, v136
	v_rcp_f32_e32 v136, v136
	v_mul_f32_e32 v135, v135, v134
	v_mul_f32_e32 v137, v137, v136
	v_cvt_pk_bf16_f32 v134, v0, v139
	v_cvt_pk_bf16_f32 v135, v141, v135
	v_cvt_pk_bf16_f32 v136, v138, v140
	v_cvt_pk_bf16_f32 v137, v142, v137
	global_store_dwordx4 v[132:133], v[134:137], off offset:64
	s_nop 1
	v_or_b32_e32 v134, 16, v170
	v_ashrrev_i32_e32 v135, 31, v134
	v_lshlrev_b64 v[132:133], 11, v[134:135]
	v_lshlrev_b64 v[134:135], 6, v[134:135]
	v_lshl_add_u64 v[146:147], s[92:93], 0, v[134:135]
	global_load_dwordx4 v[134:137], v[146:147], off offset:32
	global_load_dwordx4 v[138:141], v[146:147], off offset:48
	global_load_dwordx4 v[142:145], v[146:147], off
	s_nop 0
	global_load_dwordx4 v[146:149], v[146:147], off offset:16
	v_lshl_add_u64 v[132:133], v[130:131], 0, v[132:133]
	s_waitcnt vmcnt(2)
	v_pk_add_f32 v[136:137], v[136:137], v[140:141]
	v_pk_add_f32 v[134:135], v[134:135], v[138:139]
	s_waitcnt vmcnt(0)
	v_pk_add_f32 v[144:145], v[144:145], v[148:149]
	v_pk_add_f32 v[142:143], v[142:143], v[146:147]
	v_pk_add_f32 v[136:137], v[144:145], v[136:137]
	v_pk_add_f32 v[134:135], v[142:143], v[134:135]
	s_nop 0
	v_pk_mov_b32 v[138:139], v[134:135], v[136:137] op_sel:[1,0]
	v_mov_b32_e32 v135, v137
	v_pk_add_f32 v[134:135], v[138:139], v[134:135]
	s_nop 0
	v_add_f32_e32 v0, v134, v135
	v_fmamk_f32 v0, v0, 0x3a800000, v211
	v_rsq_f32_e32 v0, v0
	s_nop 0
	v_pk_mul_f32 v[138:139], v[114:115], v[0:1] op_sel_hi:[1,0]
	v_pk_mul_f32 v[140:141], v[106:107], v[0:1] op_sel_hi:[1,0]
	v_mul_f32_e32 v142, 0xbfb8aa3b, v138
	v_exp_f32_e32 v142, v142
	v_mul_f32_e32 v143, 0xbfb8aa3b, v140
	v_exp_f32_e32 v143, v143
	v_pk_mul_f32 v[134:135], v[116:117], v[0:1] op_sel_hi:[1,0]
	v_add_f32_e32 v142, 1.0, v142
	v_rcp_f32_e32 v142, v142
	v_add_f32_e32 v143, 1.0, v143
	v_rcp_f32_e32 v143, v143
	v_pk_mul_f32 v[136:137], v[108:109], v[0:1] op_sel_hi:[1,0]
	v_mul_f32_e32 v138, v138, v142
	v_mul_f32_e32 v140, v140, v143
	v_mul_f32_e32 v142, 0xbfb8aa3b, v139
	v_exp_f32_e32 v142, v142
	v_mul_f32_e32 v143, 0xbfb8aa3b, v141
	v_exp_f32_e32 v143, v143
	v_add_f32_e32 v142, 1.0, v142
	v_rcp_f32_e32 v142, v142
	v_add_f32_e32 v143, 1.0, v143
	v_rcp_f32_e32 v143, v143
	v_mul_f32_e32 v139, v139, v142
	v_mul_f32_e32 v141, v141, v143
	v_mul_f32_e32 v142, 0xbfb8aa3b, v134
	v_exp_f32_e32 v142, v142
	v_mul_f32_e32 v143, 0xbfb8aa3b, v136
	v_exp_f32_e32 v143, v143
	v_add_f32_e32 v142, 1.0, v142
	v_rcp_f32_e32 v142, v142
	v_add_f32_e32 v143, 1.0, v143
	v_rcp_f32_e32 v143, v143
	v_mul_f32_e32 v142, v134, v142
	v_mul_f32_e32 v143, v136, v143
	v_mul_f32_e32 v134, 0xbfb8aa3b, v135
	v_exp_f32_e32 v134, v134
	v_mul_f32_e32 v136, 0xbfb8aa3b, v137
	v_exp_f32_e32 v136, v136
	v_add_f32_e32 v134, 1.0, v134
	v_rcp_f32_e32 v134, v134
	v_add_f32_e32 v136, 1.0, v136
	v_rcp_f32_e32 v136, v136
	v_mul_f32_e32 v135, v135, v134
	v_mul_f32_e32 v137, v137, v136
	v_cvt_pk_bf16_f32 v134, v138, v139
	v_cvt_pk_bf16_f32 v135, v142, v135
	v_cvt_pk_bf16_f32 v136, v140, v141
	v_cvt_pk_bf16_f32 v137, v143, v137
	global_store_dwordx4 v[132:133], v[134:137], off
	v_pk_mul_f32 v[138:139], v[96:97], v[0:1] op_sel_hi:[1,0]
	v_pk_mul_f32 v[140:141], v[94:95], v[0:1] op_sel_hi:[1,0]
	v_pk_mul_f32 v[136:137], v[102:103], v[0:1] op_sel_hi:[1,0]
	v_pk_mul_f32 v[134:135], v[104:105], v[0:1] op_sel_hi:[1,0]
	v_mul_f32_e32 v0, 0xbfb8aa3b, v136
	v_exp_f32_e32 v0, v0
	v_mul_f32_e32 v142, 0xbfb8aa3b, v140
	v_exp_f32_e32 v142, v142
	v_add_f32_e32 v0, 1.0, v0
	v_rcp_f32_e32 v0, v0
	v_add_f32_e32 v142, 1.0, v142
	v_rcp_f32_e32 v142, v142
	v_mul_f32_e32 v0, v136, v0
	v_mul_f32_e32 v136, v140, v142
	v_mul_f32_e32 v140, 0xbfb8aa3b, v137
	v_exp_f32_e32 v140, v140
	v_mul_f32_e32 v142, 0xbfb8aa3b, v141
	v_exp_f32_e32 v142, v142
	v_add_f32_e32 v140, 1.0, v140
	v_rcp_f32_e32 v140, v140
	v_add_f32_e32 v142, 1.0, v142
	v_rcp_f32_e32 v142, v142
	v_mul_f32_e32 v137, v137, v140
	v_mul_f32_e32 v140, v141, v142
	v_mul_f32_e32 v141, 0xbfb8aa3b, v134
	v_exp_f32_e32 v141, v141
	v_mul_f32_e32 v142, 0xbfb8aa3b, v138
	v_exp_f32_e32 v142, v142
	v_add_f32_e32 v141, 1.0, v141
	v_rcp_f32_e32 v141, v141
	v_add_f32_e32 v142, 1.0, v142
	v_rcp_f32_e32 v142, v142
	v_mul_f32_e32 v141, v134, v141
	v_mul_f32_e32 v138, v138, v142
	v_mul_f32_e32 v134, 0xbfb8aa3b, v135
	v_exp_f32_e32 v134, v134
	v_mul_f32_e32 v142, 0xbfb8aa3b, v139
	v_exp_f32_e32 v142, v142
	v_add_f32_e32 v134, 1.0, v134
	v_rcp_f32_e32 v134, v134
	v_add_f32_e32 v142, 1.0, v142
	v_rcp_f32_e32 v142, v142
	v_mul_f32_e32 v135, v135, v134
	v_mul_f32_e32 v139, v139, v142
	v_cvt_pk_bf16_f32 v134, v0, v137
	v_cvt_pk_bf16_f32 v135, v141, v135
	v_cvt_pk_bf16_f32 v136, v136, v140
	v_cvt_pk_bf16_f32 v137, v138, v139
	global_store_dwordx4 v[132:133], v[134:137], off offset:64
	s_nop 1
	v_or_b32_e32 v134, 32, v170
	v_ashrrev_i32_e32 v135, 31, v134
	v_lshlrev_b64 v[132:133], 11, v[134:135]
	v_lshlrev_b64 v[134:135], 6, v[134:135]
	v_lshl_add_u64 v[146:147], s[92:93], 0, v[134:135]
	global_load_dwordx4 v[134:137], v[146:147], off offset:32
	global_load_dwordx4 v[138:141], v[146:147], off offset:48
	global_load_dwordx4 v[142:145], v[146:147], off
	s_nop 0
	global_load_dwordx4 v[146:149], v[146:147], off offset:16
	v_lshl_add_u64 v[132:133], v[130:131], 0, v[132:133]
	s_waitcnt vmcnt(2)
	v_pk_add_f32 v[136:137], v[136:137], v[140:141]
	v_pk_add_f32 v[134:135], v[134:135], v[138:139]
	s_waitcnt vmcnt(0)
	v_pk_add_f32 v[144:145], v[144:145], v[148:149]
	v_pk_add_f32 v[142:143], v[142:143], v[146:147]
	v_pk_add_f32 v[136:137], v[144:145], v[136:137]
	v_pk_add_f32 v[134:135], v[142:143], v[134:135]
	s_nop 0
	v_pk_mov_b32 v[138:139], v[134:135], v[136:137] op_sel:[1,0]
	v_mov_b32_e32 v135, v137
	v_pk_add_f32 v[134:135], v[138:139], v[134:135]
	s_nop 0
	v_add_f32_e32 v0, v134, v135
	v_fmamk_f32 v0, v0, 0x3a800000, v211
	v_rsq_f32_e32 v0, v0
	s_nop 0
	v_pk_mul_f32 v[136:137], v[98:99], v[0:1] op_sel_hi:[1,0]
	v_pk_mul_f32 v[140:141], v[90:91], v[0:1] op_sel_hi:[1,0]
	v_mul_f32_e32 v142, 0xbfb8aa3b, v136
	v_exp_f32_e32 v142, v142
	v_mul_f32_e32 v143, 0xbfb8aa3b, v140
	v_exp_f32_e32 v143, v143
	v_pk_mul_f32 v[134:135], v[100:101], v[0:1] op_sel_hi:[1,0]
	v_add_f32_e32 v142, 1.0, v142
	v_rcp_f32_e32 v142, v142
	v_add_f32_e32 v143, 1.0, v143
	v_rcp_f32_e32 v143, v143
	v_pk_mul_f32 v[138:139], v[92:93], v[0:1] op_sel_hi:[1,0]
	v_mul_f32_e32 v136, v136, v142
	v_mul_f32_e32 v140, v140, v143
	v_mul_f32_e32 v142, 0xbfb8aa3b, v137
	v_exp_f32_e32 v142, v142
	v_mul_f32_e32 v143, 0xbfb8aa3b, v141
	v_exp_f32_e32 v143, v143
	v_add_f32_e32 v142, 1.0, v142
	v_rcp_f32_e32 v142, v142
	v_add_f32_e32 v143, 1.0, v143
	v_rcp_f32_e32 v143, v143
	v_mul_f32_e32 v137, v137, v142
	v_mul_f32_e32 v141, v141, v143
	v_mul_f32_e32 v142, 0xbfb8aa3b, v134
	v_exp_f32_e32 v142, v142
	v_mul_f32_e32 v143, 0xbfb8aa3b, v138
	v_exp_f32_e32 v143, v143
	v_add_f32_e32 v142, 1.0, v142
	v_rcp_f32_e32 v142, v142
	v_add_f32_e32 v143, 1.0, v143
	v_rcp_f32_e32 v143, v143
	v_mul_f32_e32 v142, v134, v142
	v_mul_f32_e32 v138, v138, v143
	v_mul_f32_e32 v134, 0xbfb8aa3b, v135
	v_exp_f32_e32 v134, v134
	v_mul_f32_e32 v143, 0xbfb8aa3b, v139
	v_exp_f32_e32 v143, v143
	v_add_f32_e32 v134, 1.0, v134
	v_rcp_f32_e32 v134, v134
	v_add_f32_e32 v143, 1.0, v143
	v_rcp_f32_e32 v143, v143
	v_mul_f32_e32 v135, v135, v134
	v_mul_f32_e32 v139, v139, v143
	v_cvt_pk_bf16_f32 v134, v136, v137
	v_cvt_pk_bf16_f32 v135, v142, v135
	v_cvt_pk_bf16_f32 v136, v140, v141
	v_cvt_pk_bf16_f32 v137, v138, v139
	global_store_dwordx4 v[132:133], v[134:137], off
	v_pk_mul_f32 v[138:139], v[80:81], v[0:1] op_sel_hi:[1,0]
	v_pk_mul_f32 v[140:141], v[78:79], v[0:1] op_sel_hi:[1,0]
	v_pk_mul_f32 v[136:137], v[86:87], v[0:1] op_sel_hi:[1,0]
	v_pk_mul_f32 v[134:135], v[88:89], v[0:1] op_sel_hi:[1,0]
	v_mul_f32_e32 v0, 0xbfb8aa3b, v136
	v_exp_f32_e32 v0, v0
	v_mul_f32_e32 v142, 0xbfb8aa3b, v140
	v_exp_f32_e32 v142, v142
	v_add_f32_e32 v0, 1.0, v0
	v_rcp_f32_e32 v0, v0
	v_add_f32_e32 v142, 1.0, v142
	v_rcp_f32_e32 v142, v142
	v_mul_f32_e32 v0, v136, v0
	v_mul_f32_e32 v136, v140, v142
	v_mul_f32_e32 v140, 0xbfb8aa3b, v137
	v_exp_f32_e32 v140, v140
	v_mul_f32_e32 v142, 0xbfb8aa3b, v141
	v_exp_f32_e32 v142, v142
	v_add_f32_e32 v140, 1.0, v140
	v_rcp_f32_e32 v140, v140
	v_add_f32_e32 v142, 1.0, v142
	v_rcp_f32_e32 v142, v142
	v_mul_f32_e32 v137, v137, v140
	v_mul_f32_e32 v140, v141, v142
	v_mul_f32_e32 v141, 0xbfb8aa3b, v134
	v_exp_f32_e32 v141, v141
	v_mul_f32_e32 v142, 0xbfb8aa3b, v138
	v_exp_f32_e32 v142, v142
	v_add_f32_e32 v141, 1.0, v141
	v_rcp_f32_e32 v141, v141
	v_add_f32_e32 v142, 1.0, v142
	v_rcp_f32_e32 v142, v142
	v_mul_f32_e32 v141, v134, v141
	v_mul_f32_e32 v138, v138, v142
	v_mul_f32_e32 v134, 0xbfb8aa3b, v135
	v_exp_f32_e32 v134, v134
	v_mul_f32_e32 v142, 0xbfb8aa3b, v139
	v_exp_f32_e32 v142, v142
	v_add_f32_e32 v134, 1.0, v134
	v_rcp_f32_e32 v134, v134
	v_add_f32_e32 v142, 1.0, v142
	v_rcp_f32_e32 v142, v142
	v_mul_f32_e32 v135, v135, v134
	v_mul_f32_e32 v139, v139, v142
	v_cvt_pk_bf16_f32 v134, v0, v137
	v_cvt_pk_bf16_f32 v135, v141, v135
	v_cvt_pk_bf16_f32 v136, v136, v140
	v_cvt_pk_bf16_f32 v137, v138, v139
	global_store_dwordx4 v[132:133], v[134:137], off offset:64
	s_nop 1
	v_or_b32_e32 v134, 48, v170
	v_ashrrev_i32_e32 v135, 31, v134
	v_lshlrev_b64 v[132:133], 11, v[134:135]
	v_lshlrev_b64 v[134:135], 6, v[134:135]
	v_lshl_add_u64 v[146:147], s[92:93], 0, v[134:135]
	global_load_dwordx4 v[134:137], v[146:147], off offset:32
	global_load_dwordx4 v[138:141], v[146:147], off offset:48
	global_load_dwordx4 v[142:145], v[146:147], off
	s_nop 0
	global_load_dwordx4 v[146:149], v[146:147], off offset:16
	v_lshl_add_u64 v[132:133], v[130:131], 0, v[132:133]
	s_waitcnt vmcnt(2)
	v_pk_add_f32 v[136:137], v[136:137], v[140:141]
	v_pk_add_f32 v[134:135], v[134:135], v[138:139]
	s_waitcnt vmcnt(0)
	v_pk_add_f32 v[144:145], v[144:145], v[148:149]
	v_pk_add_f32 v[142:143], v[142:143], v[146:147]
	v_pk_add_f32 v[136:137], v[144:145], v[136:137]
	v_pk_add_f32 v[134:135], v[142:143], v[134:135]
	s_nop 0
	v_pk_mov_b32 v[138:139], v[134:135], v[136:137] op_sel:[1,0]
	v_mov_b32_e32 v135, v137
	v_pk_add_f32 v[134:135], v[138:139], v[134:135]
	s_nop 0
	v_add_f32_e32 v0, v134, v135
	v_fmamk_f32 v0, v0, 0x3a800000, v211
	v_rsq_f32_e32 v0, v0
	s_nop 0
	v_pk_mul_f32 v[136:137], v[82:83], v[0:1] op_sel_hi:[1,0]
	v_pk_mul_f32 v[140:141], v[74:75], v[0:1] op_sel_hi:[1,0]
	v_mul_f32_e32 v142, 0xbfb8aa3b, v136
	v_exp_f32_e32 v142, v142
	v_mul_f32_e32 v143, 0xbfb8aa3b, v140
	v_exp_f32_e32 v143, v143
	v_pk_mul_f32 v[134:135], v[84:85], v[0:1] op_sel_hi:[1,0]
	v_add_f32_e32 v142, 1.0, v142
	v_rcp_f32_e32 v142, v142
	v_add_f32_e32 v143, 1.0, v143
	v_rcp_f32_e32 v143, v143
	v_pk_mul_f32 v[138:139], v[76:77], v[0:1] op_sel_hi:[1,0]
	v_mul_f32_e32 v136, v136, v142
	v_mul_f32_e32 v140, v140, v143
	v_mul_f32_e32 v142, 0xbfb8aa3b, v137
	v_exp_f32_e32 v142, v142
	v_mul_f32_e32 v143, 0xbfb8aa3b, v141
	v_exp_f32_e32 v143, v143
	v_add_f32_e32 v142, 1.0, v142
	v_rcp_f32_e32 v142, v142
	v_add_f32_e32 v143, 1.0, v143
	v_rcp_f32_e32 v143, v143
	v_mul_f32_e32 v137, v137, v142
	v_mul_f32_e32 v141, v141, v143
	v_mul_f32_e32 v142, 0xbfb8aa3b, v134
	v_exp_f32_e32 v142, v142
	v_mul_f32_e32 v143, 0xbfb8aa3b, v138
	v_exp_f32_e32 v143, v143
	v_add_f32_e32 v142, 1.0, v142
	v_rcp_f32_e32 v142, v142
	v_add_f32_e32 v143, 1.0, v143
	v_rcp_f32_e32 v143, v143
	v_mul_f32_e32 v142, v134, v142
	v_mul_f32_e32 v138, v138, v143
	v_mul_f32_e32 v134, 0xbfb8aa3b, v135
	v_exp_f32_e32 v134, v134
	v_mul_f32_e32 v143, 0xbfb8aa3b, v139
	v_exp_f32_e32 v143, v143
	v_add_f32_e32 v134, 1.0, v134
	v_rcp_f32_e32 v134, v134
	v_add_f32_e32 v143, 1.0, v143
	v_rcp_f32_e32 v143, v143
	v_mul_f32_e32 v135, v135, v134
	v_mul_f32_e32 v139, v139, v143
	v_cvt_pk_bf16_f32 v134, v136, v137
	v_cvt_pk_bf16_f32 v135, v142, v135
	v_cvt_pk_bf16_f32 v136, v140, v141
	v_cvt_pk_bf16_f32 v137, v138, v139
	global_store_dwordx4 v[132:133], v[134:137], off
	v_pk_mul_f32 v[138:139], v[68:69], v[0:1] op_sel_hi:[1,0]
	v_pk_mul_f32 v[140:141], v[66:67], v[0:1] op_sel_hi:[1,0]
	v_pk_mul_f32 v[136:137], v[70:71], v[0:1] op_sel_hi:[1,0]
	v_pk_mul_f32 v[134:135], v[72:73], v[0:1] op_sel_hi:[1,0]
	v_mul_f32_e32 v0, 0xbfb8aa3b, v136
	v_exp_f32_e32 v0, v0
	v_mul_f32_e32 v142, 0xbfb8aa3b, v140
	v_exp_f32_e32 v142, v142
	v_add_f32_e32 v0, 1.0, v0
	v_rcp_f32_e32 v0, v0
	v_add_f32_e32 v142, 1.0, v142
	v_rcp_f32_e32 v142, v142
	v_mul_f32_e32 v0, v136, v0
	v_mul_f32_e32 v136, v140, v142
	v_mul_f32_e32 v140, 0xbfb8aa3b, v137
	v_exp_f32_e32 v140, v140
	v_mul_f32_e32 v142, 0xbfb8aa3b, v141
	v_exp_f32_e32 v142, v142
	v_add_f32_e32 v140, 1.0, v140
	v_rcp_f32_e32 v140, v140
	v_add_f32_e32 v142, 1.0, v142
	v_rcp_f32_e32 v142, v142
	v_mul_f32_e32 v137, v137, v140
	v_mul_f32_e32 v140, v141, v142
	v_mul_f32_e32 v141, 0xbfb8aa3b, v134
	v_exp_f32_e32 v141, v141
	v_mul_f32_e32 v142, 0xbfb8aa3b, v138
	v_exp_f32_e32 v142, v142
	v_add_f32_e32 v141, 1.0, v141
	v_rcp_f32_e32 v141, v141
	v_add_f32_e32 v142, 1.0, v142
	v_rcp_f32_e32 v142, v142
	v_mul_f32_e32 v141, v134, v141
	v_mul_f32_e32 v138, v138, v142
	v_mul_f32_e32 v134, 0xbfb8aa3b, v135
	v_exp_f32_e32 v134, v134
	v_mul_f32_e32 v142, 0xbfb8aa3b, v139
	v_exp_f32_e32 v142, v142
	v_add_f32_e32 v134, 1.0, v134
	v_rcp_f32_e32 v134, v134
	v_add_f32_e32 v142, 1.0, v142
	v_rcp_f32_e32 v142, v142
	v_mul_f32_e32 v135, v135, v134
	v_mul_f32_e32 v139, v139, v142
	v_cvt_pk_bf16_f32 v134, v0, v137
	v_cvt_pk_bf16_f32 v135, v141, v135
	v_cvt_pk_bf16_f32 v136, v136, v140
	v_cvt_pk_bf16_f32 v137, v138, v139
	global_store_dwordx4 v[132:133], v[134:137], off offset:64
	s_nop 1
	v_add_u32_e32 v134, 0x80, v170
	v_ashrrev_i32_e32 v135, 31, v134
	v_lshlrev_b64 v[132:133], 11, v[134:135]
	v_lshlrev_b64 v[134:135], 6, v[134:135]
	v_lshl_add_u64 v[146:147], s[92:93], 0, v[134:135]
	global_load_dwordx4 v[134:137], v[146:147], off offset:32
	global_load_dwordx4 v[138:141], v[146:147], off offset:48
	global_load_dwordx4 v[142:145], v[146:147], off
	s_nop 0
	global_load_dwordx4 v[146:149], v[146:147], off offset:16
	v_lshl_add_u64 v[132:133], v[130:131], 0, v[132:133]
	s_waitcnt vmcnt(2)
	v_pk_add_f32 v[136:137], v[136:137], v[140:141]
	v_pk_add_f32 v[134:135], v[134:135], v[138:139]
	s_waitcnt vmcnt(0)
	v_pk_add_f32 v[144:145], v[144:145], v[148:149]
	v_pk_add_f32 v[142:143], v[142:143], v[146:147]
	v_pk_add_f32 v[136:137], v[144:145], v[136:137]
	v_pk_add_f32 v[134:135], v[142:143], v[134:135]
	s_nop 0
	v_pk_mov_b32 v[138:139], v[134:135], v[136:137] op_sel:[1,0]
	v_mov_b32_e32 v135, v137
	v_pk_add_f32 v[134:135], v[138:139], v[134:135]
	s_nop 0
	v_add_f32_e32 v0, v134, v135
	v_fmamk_f32 v0, v0, 0x3a800000, v211
	v_rsq_f32_e32 v0, v0
	s_nop 0
	v_pk_mul_f32 v[136:137], v[62:63], v[0:1] op_sel_hi:[1,0]
	v_pk_mul_f32 v[140:141], v[58:59], v[0:1] op_sel_hi:[1,0]
	v_mul_f32_e32 v142, 0xbfb8aa3b, v136
	v_exp_f32_e32 v142, v142
	v_mul_f32_e32 v143, 0xbfb8aa3b, v140
	v_exp_f32_e32 v143, v143
	v_pk_mul_f32 v[134:135], v[64:65], v[0:1] op_sel_hi:[1,0]
	v_add_f32_e32 v142, 1.0, v142
	v_rcp_f32_e32 v142, v142
	v_add_f32_e32 v143, 1.0, v143
	v_rcp_f32_e32 v143, v143
	v_pk_mul_f32 v[138:139], v[60:61], v[0:1] op_sel_hi:[1,0]
	v_mul_f32_e32 v136, v136, v142
	v_mul_f32_e32 v140, v140, v143
	v_mul_f32_e32 v142, 0xbfb8aa3b, v137
	v_exp_f32_e32 v142, v142
	v_mul_f32_e32 v143, 0xbfb8aa3b, v141
	v_exp_f32_e32 v143, v143
	v_add_f32_e32 v142, 1.0, v142
	v_rcp_f32_e32 v142, v142
	v_add_f32_e32 v143, 1.0, v143
	v_rcp_f32_e32 v143, v143
	v_mul_f32_e32 v137, v137, v142
	v_mul_f32_e32 v141, v141, v143
	v_mul_f32_e32 v142, 0xbfb8aa3b, v134
	v_exp_f32_e32 v142, v142
	v_mul_f32_e32 v143, 0xbfb8aa3b, v138
	v_exp_f32_e32 v143, v143
	v_add_f32_e32 v142, 1.0, v142
	v_rcp_f32_e32 v142, v142
	v_add_f32_e32 v143, 1.0, v143
	v_rcp_f32_e32 v143, v143
	v_mul_f32_e32 v142, v134, v142
	v_mul_f32_e32 v138, v138, v143
	v_mul_f32_e32 v134, 0xbfb8aa3b, v135
	v_exp_f32_e32 v134, v134
	v_mul_f32_e32 v143, 0xbfb8aa3b, v139
	v_exp_f32_e32 v143, v143
	v_add_f32_e32 v134, 1.0, v134
	v_rcp_f32_e32 v134, v134
	v_add_f32_e32 v143, 1.0, v143
	v_rcp_f32_e32 v143, v143
	v_mul_f32_e32 v135, v135, v134
	v_mul_f32_e32 v139, v139, v143
	v_cvt_pk_bf16_f32 v134, v136, v137
	v_cvt_pk_bf16_f32 v135, v142, v135
	v_cvt_pk_bf16_f32 v136, v140, v141
	v_cvt_pk_bf16_f32 v137, v138, v139
	global_store_dwordx4 v[132:133], v[134:137], off
	v_pk_mul_f32 v[138:139], v[48:49], v[0:1] op_sel_hi:[1,0]
	v_pk_mul_f32 v[140:141], v[46:47], v[0:1] op_sel_hi:[1,0]
	v_pk_mul_f32 v[136:137], v[54:55], v[0:1] op_sel_hi:[1,0]
	v_pk_mul_f32 v[134:135], v[56:57], v[0:1] op_sel_hi:[1,0]
	v_mul_f32_e32 v0, 0xbfb8aa3b, v136
	v_exp_f32_e32 v0, v0
	v_mul_f32_e32 v142, 0xbfb8aa3b, v140
	v_exp_f32_e32 v142, v142
	v_add_f32_e32 v0, 1.0, v0
	v_rcp_f32_e32 v0, v0
	v_add_f32_e32 v142, 1.0, v142
	v_rcp_f32_e32 v142, v142
	v_mul_f32_e32 v0, v136, v0
	v_mul_f32_e32 v136, v140, v142
	v_mul_f32_e32 v140, 0xbfb8aa3b, v137
	v_exp_f32_e32 v140, v140
	v_mul_f32_e32 v142, 0xbfb8aa3b, v141
	v_exp_f32_e32 v142, v142
	v_add_f32_e32 v140, 1.0, v140
	v_rcp_f32_e32 v140, v140
	v_add_f32_e32 v142, 1.0, v142
	v_rcp_f32_e32 v142, v142
	v_mul_f32_e32 v137, v137, v140
	v_mul_f32_e32 v140, v141, v142
	v_mul_f32_e32 v141, 0xbfb8aa3b, v134
	v_exp_f32_e32 v141, v141
	v_mul_f32_e32 v142, 0xbfb8aa3b, v138
	v_exp_f32_e32 v142, v142
	v_add_f32_e32 v141, 1.0, v141
	v_rcp_f32_e32 v141, v141
	v_add_f32_e32 v142, 1.0, v142
	v_rcp_f32_e32 v142, v142
	v_mul_f32_e32 v141, v134, v141
	v_mul_f32_e32 v138, v138, v142
	v_mul_f32_e32 v134, 0xbfb8aa3b, v135
	v_exp_f32_e32 v134, v134
	v_mul_f32_e32 v142, 0xbfb8aa3b, v139
	v_exp_f32_e32 v142, v142
	v_add_f32_e32 v134, 1.0, v134
	v_rcp_f32_e32 v134, v134
	v_add_f32_e32 v142, 1.0, v142
	v_rcp_f32_e32 v142, v142
	v_mul_f32_e32 v135, v135, v134
	v_mul_f32_e32 v139, v139, v142
	v_cvt_pk_bf16_f32 v134, v0, v137
	v_cvt_pk_bf16_f32 v135, v141, v135
	v_cvt_pk_bf16_f32 v136, v136, v140
	v_cvt_pk_bf16_f32 v137, v138, v139
	global_store_dwordx4 v[132:133], v[134:137], off offset:64
	s_nop 1
	v_add_u32_e32 v134, 0x90, v170
	v_ashrrev_i32_e32 v135, 31, v134
	v_lshlrev_b64 v[132:133], 11, v[134:135]
	v_lshlrev_b64 v[134:135], 6, v[134:135]
	v_lshl_add_u64 v[146:147], s[92:93], 0, v[134:135]
	global_load_dwordx4 v[134:137], v[146:147], off offset:32
	global_load_dwordx4 v[138:141], v[146:147], off offset:48
	global_load_dwordx4 v[142:145], v[146:147], off
	s_nop 0
	global_load_dwordx4 v[146:149], v[146:147], off offset:16
	v_lshl_add_u64 v[132:133], v[130:131], 0, v[132:133]
	s_waitcnt vmcnt(2)
	v_pk_add_f32 v[136:137], v[136:137], v[140:141]
	v_pk_add_f32 v[134:135], v[134:135], v[138:139]
	s_waitcnt vmcnt(0)
	v_pk_add_f32 v[144:145], v[144:145], v[148:149]
	v_pk_add_f32 v[142:143], v[142:143], v[146:147]
	v_pk_add_f32 v[136:137], v[144:145], v[136:137]
	v_pk_add_f32 v[134:135], v[142:143], v[134:135]
	s_nop 0
	v_pk_mov_b32 v[138:139], v[134:135], v[136:137] op_sel:[1,0]
	v_mov_b32_e32 v135, v137
	v_pk_add_f32 v[134:135], v[138:139], v[134:135]
	s_nop 0
	v_add_f32_e32 v0, v134, v135
	v_fmamk_f32 v0, v0, 0x3a800000, v211
	v_rsq_f32_e32 v0, v0
	s_nop 0
	v_pk_mul_f32 v[136:137], v[50:51], v[0:1] op_sel_hi:[1,0]
	v_pk_mul_f32 v[140:141], v[42:43], v[0:1] op_sel_hi:[1,0]
	v_mul_f32_e32 v142, 0xbfb8aa3b, v136
	v_exp_f32_e32 v142, v142
	v_mul_f32_e32 v143, 0xbfb8aa3b, v140
	v_exp_f32_e32 v143, v143
	v_pk_mul_f32 v[134:135], v[52:53], v[0:1] op_sel_hi:[1,0]
	v_add_f32_e32 v142, 1.0, v142
	v_rcp_f32_e32 v142, v142
	v_add_f32_e32 v143, 1.0, v143
	v_rcp_f32_e32 v143, v143
	v_pk_mul_f32 v[138:139], v[44:45], v[0:1] op_sel_hi:[1,0]
	v_mul_f32_e32 v136, v136, v142
	v_mul_f32_e32 v140, v140, v143
	v_mul_f32_e32 v142, 0xbfb8aa3b, v137
	v_exp_f32_e32 v142, v142
	v_mul_f32_e32 v143, 0xbfb8aa3b, v141
	v_exp_f32_e32 v143, v143
	v_add_f32_e32 v142, 1.0, v142
	v_rcp_f32_e32 v142, v142
	v_add_f32_e32 v143, 1.0, v143
	v_rcp_f32_e32 v143, v143
	v_mul_f32_e32 v137, v137, v142
	v_mul_f32_e32 v141, v141, v143
	v_mul_f32_e32 v142, 0xbfb8aa3b, v134
	v_exp_f32_e32 v142, v142
	v_mul_f32_e32 v143, 0xbfb8aa3b, v138
	v_exp_f32_e32 v143, v143
	v_add_f32_e32 v142, 1.0, v142
	v_rcp_f32_e32 v142, v142
	v_add_f32_e32 v143, 1.0, v143
	v_rcp_f32_e32 v143, v143
	v_mul_f32_e32 v142, v134, v142
	v_mul_f32_e32 v138, v138, v143
	v_mul_f32_e32 v134, 0xbfb8aa3b, v135
	v_exp_f32_e32 v134, v134
	v_mul_f32_e32 v143, 0xbfb8aa3b, v139
	v_exp_f32_e32 v143, v143
	v_add_f32_e32 v134, 1.0, v134
	v_rcp_f32_e32 v134, v134
	v_add_f32_e32 v143, 1.0, v143
	v_rcp_f32_e32 v143, v143
	v_mul_f32_e32 v135, v135, v134
	v_mul_f32_e32 v139, v139, v143
	v_cvt_pk_bf16_f32 v134, v136, v137
	v_cvt_pk_bf16_f32 v135, v142, v135
	v_cvt_pk_bf16_f32 v136, v140, v141
	v_cvt_pk_bf16_f32 v137, v138, v139
	global_store_dwordx4 v[132:133], v[134:137], off
	v_pk_mul_f32 v[138:139], v[32:33], v[0:1] op_sel_hi:[1,0]
	v_pk_mul_f32 v[140:141], v[30:31], v[0:1] op_sel_hi:[1,0]
	v_pk_mul_f32 v[136:137], v[38:39], v[0:1] op_sel_hi:[1,0]
	v_pk_mul_f32 v[134:135], v[40:41], v[0:1] op_sel_hi:[1,0]
	v_mul_f32_e32 v0, 0xbfb8aa3b, v136
	v_exp_f32_e32 v0, v0
	v_mul_f32_e32 v142, 0xbfb8aa3b, v140
	v_exp_f32_e32 v142, v142
	v_add_f32_e32 v0, 1.0, v0
	v_rcp_f32_e32 v0, v0
	v_add_f32_e32 v142, 1.0, v142
	v_rcp_f32_e32 v142, v142
	v_mul_f32_e32 v0, v136, v0
	v_mul_f32_e32 v136, v140, v142
	v_mul_f32_e32 v140, 0xbfb8aa3b, v137
	v_exp_f32_e32 v140, v140
	v_mul_f32_e32 v142, 0xbfb8aa3b, v141
	v_exp_f32_e32 v142, v142
	v_add_f32_e32 v140, 1.0, v140
	v_rcp_f32_e32 v140, v140
	v_add_f32_e32 v142, 1.0, v142
	v_rcp_f32_e32 v142, v142
	v_mul_f32_e32 v137, v137, v140
	v_mul_f32_e32 v140, v141, v142
	v_mul_f32_e32 v141, 0xbfb8aa3b, v134
	v_exp_f32_e32 v141, v141
	v_mul_f32_e32 v142, 0xbfb8aa3b, v138
	v_exp_f32_e32 v142, v142
	v_add_f32_e32 v141, 1.0, v141
	v_rcp_f32_e32 v141, v141
	v_add_f32_e32 v142, 1.0, v142
	v_rcp_f32_e32 v142, v142
	v_mul_f32_e32 v141, v134, v141
	v_mul_f32_e32 v138, v138, v142
	v_mul_f32_e32 v134, 0xbfb8aa3b, v135
	v_exp_f32_e32 v134, v134
	v_mul_f32_e32 v142, 0xbfb8aa3b, v139
	v_exp_f32_e32 v142, v142
	v_add_f32_e32 v134, 1.0, v134
	v_rcp_f32_e32 v134, v134
	v_add_f32_e32 v142, 1.0, v142
	v_rcp_f32_e32 v142, v142
	v_mul_f32_e32 v135, v135, v134
	v_mul_f32_e32 v139, v139, v142
	v_cvt_pk_bf16_f32 v134, v0, v137
	v_cvt_pk_bf16_f32 v135, v141, v135
	v_cvt_pk_bf16_f32 v136, v136, v140
	v_cvt_pk_bf16_f32 v137, v138, v139
	global_store_dwordx4 v[132:133], v[134:137], off offset:64
	s_nop 1
	v_add_u32_e32 v134, 0xa0, v170
	v_ashrrev_i32_e32 v135, 31, v134
	v_lshlrev_b64 v[132:133], 11, v[134:135]
	v_lshlrev_b64 v[134:135], 6, v[134:135]
	v_lshl_add_u64 v[146:147], s[92:93], 0, v[134:135]
	global_load_dwordx4 v[134:137], v[146:147], off offset:32
	global_load_dwordx4 v[138:141], v[146:147], off offset:48
	global_load_dwordx4 v[142:145], v[146:147], off
	s_nop 0
	global_load_dwordx4 v[146:149], v[146:147], off offset:16
	v_lshl_add_u64 v[132:133], v[130:131], 0, v[132:133]
	s_waitcnt vmcnt(2)
	v_pk_add_f32 v[136:137], v[136:137], v[140:141]
	v_pk_add_f32 v[134:135], v[134:135], v[138:139]
	s_waitcnt vmcnt(0)
	v_pk_add_f32 v[144:145], v[144:145], v[148:149]
	v_pk_add_f32 v[142:143], v[142:143], v[146:147]
	v_pk_add_f32 v[136:137], v[144:145], v[136:137]
	v_pk_add_f32 v[134:135], v[142:143], v[134:135]
	s_nop 0
	v_pk_mov_b32 v[138:139], v[134:135], v[136:137] op_sel:[1,0]
	v_mov_b32_e32 v135, v137
	v_pk_add_f32 v[134:135], v[138:139], v[134:135]
	s_nop 0
	v_add_f32_e32 v0, v134, v135
	v_fmamk_f32 v0, v0, 0x3a800000, v211
	v_rsq_f32_e32 v0, v0
	s_nop 0
	v_pk_mul_f32 v[136:137], v[34:35], v[0:1] op_sel_hi:[1,0]
	v_pk_mul_f32 v[140:141], v[26:27], v[0:1] op_sel_hi:[1,0]
	v_mul_f32_e32 v142, 0xbfb8aa3b, v136
	v_exp_f32_e32 v142, v142
	v_mul_f32_e32 v143, 0xbfb8aa3b, v140
	v_exp_f32_e32 v143, v143
	v_pk_mul_f32 v[134:135], v[36:37], v[0:1] op_sel_hi:[1,0]
	v_add_f32_e32 v142, 1.0, v142
	v_rcp_f32_e32 v142, v142
	v_add_f32_e32 v143, 1.0, v143
	v_rcp_f32_e32 v143, v143
	v_pk_mul_f32 v[138:139], v[28:29], v[0:1] op_sel_hi:[1,0]
	v_mul_f32_e32 v136, v136, v142
	v_mul_f32_e32 v140, v140, v143
	v_mul_f32_e32 v142, 0xbfb8aa3b, v137
	v_exp_f32_e32 v142, v142
	v_mul_f32_e32 v143, 0xbfb8aa3b, v141
	v_exp_f32_e32 v143, v143
	v_add_f32_e32 v142, 1.0, v142
	v_rcp_f32_e32 v142, v142
	v_add_f32_e32 v143, 1.0, v143
	v_rcp_f32_e32 v143, v143
	v_mul_f32_e32 v137, v137, v142
	v_mul_f32_e32 v141, v141, v143
	v_mul_f32_e32 v142, 0xbfb8aa3b, v134
	v_exp_f32_e32 v142, v142
	v_mul_f32_e32 v143, 0xbfb8aa3b, v138
	v_exp_f32_e32 v143, v143
	v_add_f32_e32 v142, 1.0, v142
	v_rcp_f32_e32 v142, v142
	v_add_f32_e32 v143, 1.0, v143
	v_rcp_f32_e32 v143, v143
	v_mul_f32_e32 v142, v134, v142
	v_mul_f32_e32 v138, v138, v143
	v_mul_f32_e32 v134, 0xbfb8aa3b, v135
	v_exp_f32_e32 v134, v134
	v_mul_f32_e32 v143, 0xbfb8aa3b, v139
	v_exp_f32_e32 v143, v143
	v_add_f32_e32 v134, 1.0, v134
	v_rcp_f32_e32 v134, v134
	v_add_f32_e32 v143, 1.0, v143
	v_rcp_f32_e32 v143, v143
	v_mul_f32_e32 v135, v135, v134
	v_mul_f32_e32 v139, v139, v143
	v_cvt_pk_bf16_f32 v134, v136, v137
	v_cvt_pk_bf16_f32 v135, v142, v135
	v_cvt_pk_bf16_f32 v136, v140, v141
	v_cvt_pk_bf16_f32 v137, v138, v139
	global_store_dwordx4 v[132:133], v[134:137], off
	v_pk_mul_f32 v[138:139], v[16:17], v[0:1] op_sel_hi:[1,0]
	v_pk_mul_f32 v[140:141], v[14:15], v[0:1] op_sel_hi:[1,0]
	v_pk_mul_f32 v[136:137], v[22:23], v[0:1] op_sel_hi:[1,0]
	v_pk_mul_f32 v[134:135], v[24:25], v[0:1] op_sel_hi:[1,0]
	v_mul_f32_e32 v0, 0xbfb8aa3b, v136
	v_exp_f32_e32 v0, v0
	v_mul_f32_e32 v142, 0xbfb8aa3b, v140
	v_exp_f32_e32 v142, v142
	v_add_f32_e32 v0, 1.0, v0
	v_rcp_f32_e32 v0, v0
	v_add_f32_e32 v142, 1.0, v142
	v_rcp_f32_e32 v142, v142
	v_mul_f32_e32 v0, v136, v0
	v_mul_f32_e32 v136, v140, v142
	v_mul_f32_e32 v140, 0xbfb8aa3b, v137
	v_exp_f32_e32 v140, v140
	v_mul_f32_e32 v142, 0xbfb8aa3b, v141
	v_exp_f32_e32 v142, v142
	v_add_f32_e32 v140, 1.0, v140
	v_rcp_f32_e32 v140, v140
	v_add_f32_e32 v142, 1.0, v142
	v_rcp_f32_e32 v142, v142
	v_mul_f32_e32 v137, v137, v140
	v_mul_f32_e32 v140, v141, v142
	v_mul_f32_e32 v141, 0xbfb8aa3b, v134
	v_exp_f32_e32 v141, v141
	v_mul_f32_e32 v142, 0xbfb8aa3b, v138
	v_exp_f32_e32 v142, v142
	v_add_f32_e32 v141, 1.0, v141
	v_rcp_f32_e32 v141, v141
	v_add_f32_e32 v142, 1.0, v142
	v_rcp_f32_e32 v142, v142
	v_mul_f32_e32 v141, v134, v141
	v_mul_f32_e32 v138, v138, v142
	v_mul_f32_e32 v134, 0xbfb8aa3b, v135
	v_exp_f32_e32 v134, v134
	v_mul_f32_e32 v142, 0xbfb8aa3b, v139
	v_exp_f32_e32 v142, v142
	v_add_f32_e32 v134, 1.0, v134
	v_rcp_f32_e32 v134, v134
	v_add_f32_e32 v142, 1.0, v142
	v_rcp_f32_e32 v142, v142
	v_mul_f32_e32 v135, v135, v134
	v_mul_f32_e32 v139, v139, v142
	v_cvt_pk_bf16_f32 v134, v0, v137
	v_cvt_pk_bf16_f32 v135, v141, v135
	v_cvt_pk_bf16_f32 v136, v136, v140
	v_cvt_pk_bf16_f32 v137, v138, v139
	global_store_dwordx4 v[132:133], v[134:137], off offset:64
	v_add_u32_e32 v132, 0xb0, v170
	v_ashrrev_i32_e32 v133, 31, v132
	v_lshlrev_b64 v[134:135], 11, v[132:133]
	v_lshlrev_b64 v[132:133], 6, v[132:133]
	v_lshl_add_u64 v[144:145], s[92:93], 0, v[132:133]
	v_lshl_add_u64 v[130:131], v[130:131], 0, v[134:135]
	global_load_dwordx4 v[132:135], v[144:145], off offset:32
	global_load_dwordx4 v[136:139], v[144:145], off offset:48
	global_load_dwordx4 v[140:143], v[144:145], off
	s_nop 0
	global_load_dwordx4 v[144:147], v[144:145], off offset:16
	s_waitcnt vmcnt(2)
	v_pk_add_f32 v[134:135], v[134:135], v[138:139]
	v_pk_add_f32 v[132:133], v[132:133], v[136:137]
	s_waitcnt vmcnt(0)
	v_pk_add_f32 v[142:143], v[142:143], v[146:147]
	v_pk_add_f32 v[140:141], v[140:141], v[144:145]
	v_pk_add_f32 v[134:135], v[142:143], v[134:135]
	v_pk_add_f32 v[132:133], v[140:141], v[132:133]
	s_nop 0
	v_pk_mov_b32 v[136:137], v[132:133], v[134:135] op_sel:[1,0]
	v_mov_b32_e32 v133, v135
	v_pk_add_f32 v[132:133], v[136:137], v[132:133]
	s_nop 0
	v_add_f32_e32 v0, v132, v133
	v_fmamk_f32 v0, v0, 0x3a800000, v211
	v_rsq_f32_e32 v0, v0
	s_nop 0
	v_pk_mul_f32 v[134:135], v[18:19], v[0:1] op_sel_hi:[1,0]
	v_pk_mul_f32 v[138:139], v[10:11], v[0:1] op_sel_hi:[1,0]
	v_mul_f32_e32 v140, 0xbfb8aa3b, v134
	v_exp_f32_e32 v140, v140
	v_mul_f32_e32 v141, 0xbfb8aa3b, v138
	v_exp_f32_e32 v141, v141
	v_pk_mul_f32 v[132:133], v[20:21], v[0:1] op_sel_hi:[1,0]
	v_add_f32_e32 v140, 1.0, v140
	v_rcp_f32_e32 v140, v140
	v_add_f32_e32 v141, 1.0, v141
	v_rcp_f32_e32 v141, v141
	v_pk_mul_f32 v[136:137], v[12:13], v[0:1] op_sel_hi:[1,0]
	v_mul_f32_e32 v134, v134, v140
	v_mul_f32_e32 v138, v138, v141
	v_mul_f32_e32 v140, 0xbfb8aa3b, v135
	v_exp_f32_e32 v140, v140
	v_mul_f32_e32 v141, 0xbfb8aa3b, v139
	v_exp_f32_e32 v141, v141
	v_add_f32_e32 v140, 1.0, v140
	v_rcp_f32_e32 v140, v140
	v_add_f32_e32 v141, 1.0, v141
	v_rcp_f32_e32 v141, v141
	v_mul_f32_e32 v135, v135, v140
	v_mul_f32_e32 v139, v139, v141
	v_mul_f32_e32 v140, 0xbfb8aa3b, v132
	v_exp_f32_e32 v140, v140
	v_mul_f32_e32 v141, 0xbfb8aa3b, v136
	v_exp_f32_e32 v141, v141
	v_add_f32_e32 v140, 1.0, v140
	v_rcp_f32_e32 v140, v140
	v_add_f32_e32 v141, 1.0, v141
	v_rcp_f32_e32 v141, v141
	v_mul_f32_e32 v140, v132, v140
	v_mul_f32_e32 v136, v136, v141
	v_mul_f32_e32 v132, 0xbfb8aa3b, v133
	v_exp_f32_e32 v132, v132
	v_mul_f32_e32 v141, 0xbfb8aa3b, v137
	v_exp_f32_e32 v141, v141
	v_add_f32_e32 v132, 1.0, v132
	v_rcp_f32_e32 v132, v132
	v_add_f32_e32 v141, 1.0, v141
	v_rcp_f32_e32 v141, v141
	v_mul_f32_e32 v133, v133, v132
	v_mul_f32_e32 v137, v137, v141
	v_cvt_pk_bf16_f32 v132, v134, v135
	v_cvt_pk_bf16_f32 v133, v140, v133
	v_cvt_pk_bf16_f32 v134, v138, v139
	v_cvt_pk_bf16_f32 v135, v136, v137
	global_store_dwordx4 v[130:131], v[132:135], off
	v_pk_mul_f32 v[136:137], v[4:5], v[0:1] op_sel_hi:[1,0]
	v_pk_mul_f32 v[138:139], v[2:3], v[0:1] op_sel_hi:[1,0]
	v_pk_mul_f32 v[134:135], v[6:7], v[0:1] op_sel_hi:[1,0]
	v_pk_mul_f32 v[132:133], v[8:9], v[0:1] op_sel_hi:[1,0]
	v_mul_f32_e32 v0, 0xbfb8aa3b, v134
	v_exp_f32_e32 v0, v0
	v_mul_f32_e32 v140, 0xbfb8aa3b, v138
	v_exp_f32_e32 v140, v140
	v_add_f32_e32 v0, 1.0, v0
	v_rcp_f32_e32 v0, v0
	v_add_f32_e32 v140, 1.0, v140
	v_rcp_f32_e32 v140, v140
	v_mul_f32_e32 v0, v134, v0
	v_mul_f32_e32 v134, v138, v140
	v_mul_f32_e32 v138, 0xbfb8aa3b, v135
	v_exp_f32_e32 v138, v138
	v_mul_f32_e32 v140, 0xbfb8aa3b, v139
	v_exp_f32_e32 v140, v140
	v_add_f32_e32 v138, 1.0, v138
	v_rcp_f32_e32 v138, v138
	v_add_f32_e32 v140, 1.0, v140
	v_rcp_f32_e32 v140, v140
	v_mul_f32_e32 v135, v135, v138
	v_mul_f32_e32 v138, v139, v140
	v_mul_f32_e32 v139, 0xbfb8aa3b, v132
	v_exp_f32_e32 v139, v139
	v_mul_f32_e32 v140, 0xbfb8aa3b, v136
	v_exp_f32_e32 v140, v140
	v_add_f32_e32 v139, 1.0, v139
	v_rcp_f32_e32 v139, v139
	v_add_f32_e32 v140, 1.0, v140
	v_rcp_f32_e32 v140, v140
	v_mul_f32_e32 v139, v132, v139
	v_mul_f32_e32 v136, v136, v140
	v_mul_f32_e32 v132, 0xbfb8aa3b, v133
	v_exp_f32_e32 v132, v132
	v_mul_f32_e32 v140, 0xbfb8aa3b, v137
	v_exp_f32_e32 v140, v140
	v_add_f32_e32 v132, 1.0, v132
	v_rcp_f32_e32 v132, v132
	v_add_f32_e32 v140, 1.0, v140
	v_rcp_f32_e32 v140, v140
	v_mul_f32_e32 v133, v133, v132
	v_mul_f32_e32 v137, v137, v140
	v_cvt_pk_bf16_f32 v132, v0, v135
	v_cvt_pk_bf16_f32 v133, v139, v133
	v_cvt_pk_bf16_f32 v134, v134, v138
	v_cvt_pk_bf16_f32 v135, v136, v137
	global_store_dwordx4 v[130:131], v[132:135], off offset:64
	s_branch .Lsig_join
.Lsig_ng:
	s_waitcnt vmcnt(0)
	v_pk_add_f32 v[136:137], v[136:137], v[140:141]
	v_pk_add_f32 v[134:135], v[134:135], v[138:139]
	v_pk_add_f32 v[144:145], v[144:145], v[148:149]
	v_pk_add_f32 v[142:143], v[142:143], v[146:147]
	v_pk_add_f32 v[136:137], v[144:145], v[136:137]
	v_pk_add_f32 v[134:135], v[142:143], v[134:135]
	s_nop 0
	v_pk_mov_b32 v[138:139], v[134:135], v[136:137] op_sel:[1,0]
	v_mov_b32_e32 v135, v137
	v_pk_add_f32 v[134:135], v[138:139], v[134:135]
	s_nop 0
	v_add_f32_e32 v0, v134, v135
	v_fmamk_f32 v0, v0, 0x3a800000, v211
	v_rsq_f32_e32 v0, v0
	s_nop 0
	v_pk_mul_f32 v[136:137], v[126:127], v[0:1] op_sel_hi:[1,0]
	v_pk_mul_f32 v[140:141], v[122:123], v[0:1] op_sel_hi:[1,0]
	v_mul_f32_e32 v142, 0xbfb8aa3b, v136
	v_exp_f32_e32 v142, v142
	v_mul_f32_e32 v143, 0xbfb8aa3b, v140
	v_exp_f32_e32 v143, v143
	v_pk_mul_f32 v[134:135], v[128:129], v[0:1] op_sel_hi:[1,0]
	v_add_f32_e32 v142, 1.0, v142
	v_rcp_f32_e32 v142, v142
	v_add_f32_e32 v143, 1.0, v143
	v_rcp_f32_e32 v143, v143
	v_pk_mul_f32 v[138:139], v[124:125], v[0:1] op_sel_hi:[1,0]
	v_mov_b32_e32 v136, v142
	v_mul_f32_e32 v142, 0xbfb8aa3b, v137
	v_mov_b32_e32 v140, v143
	v_exp_f32_e32 v142, v142
	v_mul_f32_e32 v143, 0xbfb8aa3b, v141
	v_exp_f32_e32 v143, v143
	v_add_f32_e32 v142, 1.0, v142
	v_rcp_f32_e32 v142, v142
	v_add_f32_e32 v143, 1.0, v143
	v_rcp_f32_e32 v143, v143
	v_mov_b32_e32 v137, v142
	v_mul_f32_e32 v142, 0xbfb8aa3b, v134
	v_mov_b32_e32 v141, v143
	v_exp_f32_e32 v142, v142
	v_mul_f32_e32 v143, 0xbfb8aa3b, v138
	v_exp_f32_e32 v143, v143
	v_add_f32_e32 v142, 1.0, v142
	v_rcp_f32_e32 v142, v142
	v_add_f32_e32 v143, 1.0, v143
	v_rcp_f32_e32 v143, v143
	s_nop 0
	v_mov_b32_e32 v138, v143
	v_mul_f32_e32 v134, 0xbfb8aa3b, v135
	v_exp_f32_e32 v134, v134
	v_mul_f32_e32 v143, 0xbfb8aa3b, v139
	v_exp_f32_e32 v143, v143
	v_add_f32_e32 v134, 1.0, v134
	v_rcp_f32_e32 v134, v134
	v_add_f32_e32 v143, 1.0, v143
	v_rcp_f32_e32 v143, v143
	v_mov_b32_e32 v135, v134
	v_mov_b32_e32 v139, v143
	v_cvt_pk_bf16_f32 v134, v136, v137
	v_cvt_pk_bf16_f32 v135, v142, v135
	v_cvt_pk_bf16_f32 v136, v140, v141
	v_cvt_pk_bf16_f32 v137, v138, v139
	v_pk_mul_f32 v[138:139], v[118:119], v[0:1] op_sel_hi:[1,0]
	global_store_dwordx4 v[132:133], v[134:137], off
	v_pk_mul_f32 v[140:141], v[110:111], v[0:1] op_sel_hi:[1,0]
	s_nop 0
	v_pk_mul_f32 v[134:135], v[120:121], v[0:1] op_sel_hi:[1,0]
	v_pk_mul_f32 v[136:137], v[112:113], v[0:1] op_sel_hi:[1,0]
	v_mul_f32_e32 v0, 0xbfb8aa3b, v138
	v_exp_f32_e32 v0, v0
	v_mul_f32_e32 v142, 0xbfb8aa3b, v140
	v_exp_f32_e32 v142, v142
	v_add_f32_e32 v0, 1.0, v0
	v_rcp_f32_e32 v0, v0
	v_add_f32_e32 v142, 1.0, v142
	v_rcp_f32_e32 v142, v142
	v_mul_f32_e32 v140, 0xbfb8aa3b, v139
	v_mov_b32_e32 v138, v142
	v_exp_f32_e32 v140, v140
	v_mul_f32_e32 v142, 0xbfb8aa3b, v141
	v_exp_f32_e32 v142, v142
	v_add_f32_e32 v140, 1.0, v140
	v_rcp_f32_e32 v140, v140
	v_add_f32_e32 v142, 1.0, v142
	v_rcp_f32_e32 v142, v142
	v_mov_b32_e32 v139, v140
	v_mul_f32_e32 v141, 0xbfb8aa3b, v134
	v_mov_b32_e32 v140, v142
	v_exp_f32_e32 v141, v141
	v_mul_f32_e32 v142, 0xbfb8aa3b, v136
	v_exp_f32_e32 v142, v142
	v_add_f32_e32 v141, 1.0, v141
	v_rcp_f32_e32 v141, v141
	v_add_f32_e32 v142, 1.0, v142
	v_rcp_f32_e32 v142, v142
	v_mul_f32_e32 v134, 0xbfb8aa3b, v135
	v_exp_f32_e32 v134, v134
	v_mul_f32_e32 v136, 0xbfb8aa3b, v137
	v_exp_f32_e32 v136, v136
	v_add_f32_e32 v134, 1.0, v134
	v_rcp_f32_e32 v134, v134
	v_add_f32_e32 v136, 1.0, v136
	v_rcp_f32_e32 v136, v136
	v_mov_b32_e32 v135, v134
	v_mov_b32_e32 v137, v136
	v_cvt_pk_bf16_f32 v134, v0, v139
	v_cvt_pk_bf16_f32 v135, v141, v135
	v_cvt_pk_bf16_f32 v136, v138, v140
	v_cvt_pk_bf16_f32 v137, v142, v137
	global_store_dwordx4 v[132:133], v[134:137], off offset:64
	s_nop 1
	v_or_b32_e32 v134, 16, v170
	v_ashrrev_i32_e32 v135, 31, v134
	v_lshlrev_b64 v[132:133], 11, v[134:135]
	v_lshlrev_b64 v[134:135], 6, v[134:135]
	v_lshl_add_u64 v[146:147], s[92:93], 0, v[134:135]
	global_load_dwordx4 v[134:137], v[146:147], off offset:32
	global_load_dwordx4 v[138:141], v[146:147], off offset:48
	global_load_dwordx4 v[142:145], v[146:147], off
	s_nop 0
	global_load_dwordx4 v[146:149], v[146:147], off offset:16
	v_lshl_add_u64 v[132:133], v[130:131], 0, v[132:133]
	s_waitcnt vmcnt(2)
	v_pk_add_f32 v[136:137], v[136:137], v[140:141]
	v_pk_add_f32 v[134:135], v[134:135], v[138:139]
	s_waitcnt vmcnt(0)
	v_pk_add_f32 v[144:145], v[144:145], v[148:149]
	v_pk_add_f32 v[142:143], v[142:143], v[146:147]
	v_pk_add_f32 v[136:137], v[144:145], v[136:137]
	v_pk_add_f32 v[134:135], v[142:143], v[134:135]
	s_nop 0
	v_pk_mov_b32 v[138:139], v[134:135], v[136:137] op_sel:[1,0]
	v_mov_b32_e32 v135, v137
	v_pk_add_f32 v[134:135], v[138:139], v[134:135]
	s_nop 0
	v_add_f32_e32 v0, v134, v135
	v_fmamk_f32 v0, v0, 0x3a800000, v211
	v_rsq_f32_e32 v0, v0
	s_nop 0
	v_pk_mul_f32 v[138:139], v[114:115], v[0:1] op_sel_hi:[1,0]
	v_pk_mul_f32 v[140:141], v[106:107], v[0:1] op_sel_hi:[1,0]
	v_mul_f32_e32 v142, 0xbfb8aa3b, v138
	v_exp_f32_e32 v142, v142
	v_mul_f32_e32 v143, 0xbfb8aa3b, v140
	v_exp_f32_e32 v143, v143
	v_pk_mul_f32 v[134:135], v[116:117], v[0:1] op_sel_hi:[1,0]
	v_add_f32_e32 v142, 1.0, v142
	v_rcp_f32_e32 v142, v142
	v_add_f32_e32 v143, 1.0, v143
	v_rcp_f32_e32 v143, v143
	v_pk_mul_f32 v[136:137], v[108:109], v[0:1] op_sel_hi:[1,0]
	v_mov_b32_e32 v138, v142
	v_mul_f32_e32 v142, 0xbfb8aa3b, v139
	v_mov_b32_e32 v140, v143
	v_exp_f32_e32 v142, v142
	v_mul_f32_e32 v143, 0xbfb8aa3b, v141
	v_exp_f32_e32 v143, v143
	v_add_f32_e32 v142, 1.0, v142
	v_rcp_f32_e32 v142, v142
	v_add_f32_e32 v143, 1.0, v143
	v_rcp_f32_e32 v143, v143
	v_mov_b32_e32 v139, v142
	v_mul_f32_e32 v142, 0xbfb8aa3b, v134
	v_mov_b32_e32 v141, v143
	v_exp_f32_e32 v142, v142
	v_mul_f32_e32 v143, 0xbfb8aa3b, v136
	v_exp_f32_e32 v143, v143
	v_add_f32_e32 v142, 1.0, v142
	v_rcp_f32_e32 v142, v142
	v_add_f32_e32 v143, 1.0, v143
	v_rcp_f32_e32 v143, v143
	v_mul_f32_e32 v134, 0xbfb8aa3b, v135
	v_exp_f32_e32 v134, v134
	v_mul_f32_e32 v136, 0xbfb8aa3b, v137
	v_exp_f32_e32 v136, v136
	v_add_f32_e32 v134, 1.0, v134
	v_rcp_f32_e32 v134, v134
	v_add_f32_e32 v136, 1.0, v136
	v_rcp_f32_e32 v136, v136
	v_mov_b32_e32 v135, v134
	v_mov_b32_e32 v137, v136
	v_cvt_pk_bf16_f32 v134, v138, v139
	v_cvt_pk_bf16_f32 v135, v142, v135
	v_cvt_pk_bf16_f32 v136, v140, v141
	v_cvt_pk_bf16_f32 v137, v143, v137
	global_store_dwordx4 v[132:133], v[134:137], off
	v_pk_mul_f32 v[138:139], v[96:97], v[0:1] op_sel_hi:[1,0]
	v_pk_mul_f32 v[140:141], v[94:95], v[0:1] op_sel_hi:[1,0]
	v_pk_mul_f32 v[136:137], v[102:103], v[0:1] op_sel_hi:[1,0]
	v_pk_mul_f32 v[134:135], v[104:105], v[0:1] op_sel_hi:[1,0]
	v_mul_f32_e32 v0, 0xbfb8aa3b, v136
	v_exp_f32_e32 v0, v0
	v_mul_f32_e32 v142, 0xbfb8aa3b, v140
	v_exp_f32_e32 v142, v142
	v_add_f32_e32 v0, 1.0, v0
	v_rcp_f32_e32 v0, v0
	v_add_f32_e32 v142, 1.0, v142
	v_rcp_f32_e32 v142, v142
	v_mul_f32_e32 v140, 0xbfb8aa3b, v137
	v_mov_b32_e32 v136, v142
	v_exp_f32_e32 v140, v140
	v_mul_f32_e32 v142, 0xbfb8aa3b, v141
	v_exp_f32_e32 v142, v142
	v_add_f32_e32 v140, 1.0, v140
	v_rcp_f32_e32 v140, v140
	v_add_f32_e32 v142, 1.0, v142
	v_rcp_f32_e32 v142, v142
	v_mov_b32_e32 v137, v140
	v_mul_f32_e32 v141, 0xbfb8aa3b, v134
	v_mov_b32_e32 v140, v142
	v_exp_f32_e32 v141, v141
	v_mul_f32_e32 v142, 0xbfb8aa3b, v138
	v_exp_f32_e32 v142, v142
	v_add_f32_e32 v141, 1.0, v141
	v_rcp_f32_e32 v141, v141
	v_add_f32_e32 v142, 1.0, v142
	v_rcp_f32_e32 v142, v142
	s_nop 0
	v_mov_b32_e32 v138, v142
	v_mul_f32_e32 v134, 0xbfb8aa3b, v135
	v_exp_f32_e32 v134, v134
	v_mul_f32_e32 v142, 0xbfb8aa3b, v139
	v_exp_f32_e32 v142, v142
	v_add_f32_e32 v134, 1.0, v134
	v_rcp_f32_e32 v134, v134
	v_add_f32_e32 v142, 1.0, v142
	v_rcp_f32_e32 v142, v142
	v_mov_b32_e32 v135, v134
	v_mov_b32_e32 v139, v142
	v_cvt_pk_bf16_f32 v134, v0, v137
	v_cvt_pk_bf16_f32 v135, v141, v135
	v_cvt_pk_bf16_f32 v136, v136, v140
	v_cvt_pk_bf16_f32 v137, v138, v139
	global_store_dwordx4 v[132:133], v[134:137], off offset:64
	s_nop 1
	v_or_b32_e32 v134, 32, v170
	v_ashrrev_i32_e32 v135, 31, v134
	v_lshlrev_b64 v[132:133], 11, v[134:135]
	v_lshlrev_b64 v[134:135], 6, v[134:135]
	v_lshl_add_u64 v[146:147], s[92:93], 0, v[134:135]
	global_load_dwordx4 v[134:137], v[146:147], off offset:32
	global_load_dwordx4 v[138:141], v[146:147], off offset:48
	global_load_dwordx4 v[142:145], v[146:147], off
	s_nop 0
	global_load_dwordx4 v[146:149], v[146:147], off offset:16
	v_lshl_add_u64 v[132:133], v[130:131], 0, v[132:133]
	s_waitcnt vmcnt(2)
	v_pk_add_f32 v[136:137], v[136:137], v[140:141]
	v_pk_add_f32 v[134:135], v[134:135], v[138:139]
	s_waitcnt vmcnt(0)
	v_pk_add_f32 v[144:145], v[144:145], v[148:149]
	v_pk_add_f32 v[142:143], v[142:143], v[146:147]
	v_pk_add_f32 v[136:137], v[144:145], v[136:137]
	v_pk_add_f32 v[134:135], v[142:143], v[134:135]
	s_nop 0
	v_pk_mov_b32 v[138:139], v[134:135], v[136:137] op_sel:[1,0]
	v_mov_b32_e32 v135, v137
	v_pk_add_f32 v[134:135], v[138:139], v[134:135]
	s_nop 0
	v_add_f32_e32 v0, v134, v135
	v_fmamk_f32 v0, v0, 0x3a800000, v211
	v_rsq_f32_e32 v0, v0
	s_nop 0
	v_pk_mul_f32 v[136:137], v[98:99], v[0:1] op_sel_hi:[1,0]
	v_pk_mul_f32 v[140:141], v[90:91], v[0:1] op_sel_hi:[1,0]
	v_mul_f32_e32 v142, 0xbfb8aa3b, v136
	v_exp_f32_e32 v142, v142
	v_mul_f32_e32 v143, 0xbfb8aa3b, v140
	v_exp_f32_e32 v143, v143
	v_pk_mul_f32 v[134:135], v[100:101], v[0:1] op_sel_hi:[1,0]
	v_add_f32_e32 v142, 1.0, v142
	v_rcp_f32_e32 v142, v142
	v_add_f32_e32 v143, 1.0, v143
	v_rcp_f32_e32 v143, v143
	v_pk_mul_f32 v[138:139], v[92:93], v[0:1] op_sel_hi:[1,0]
	v_mov_b32_e32 v136, v142
	v_mul_f32_e32 v142, 0xbfb8aa3b, v137
	v_mov_b32_e32 v140, v143
	v_exp_f32_e32 v142, v142
	v_mul_f32_e32 v143, 0xbfb8aa3b, v141
	v_exp_f32_e32 v143, v143
	v_add_f32_e32 v142, 1.0, v142
	v_rcp_f32_e32 v142, v142
	v_add_f32_e32 v143, 1.0, v143
	v_rcp_f32_e32 v143, v143
	v_mov_b32_e32 v137, v142
	v_mul_f32_e32 v142, 0xbfb8aa3b, v134
	v_mov_b32_e32 v141, v143
	v_exp_f32_e32 v142, v142
	v_mul_f32_e32 v143, 0xbfb8aa3b, v138
	v_exp_f32_e32 v143, v143
	v_add_f32_e32 v142, 1.0, v142
	v_rcp_f32_e32 v142, v142
	v_add_f32_e32 v143, 1.0, v143
	v_rcp_f32_e32 v143, v143
	s_nop 0
	v_mov_b32_e32 v138, v143
	v_mul_f32_e32 v134, 0xbfb8aa3b, v135
	v_exp_f32_e32 v134, v134
	v_mul_f32_e32 v143, 0xbfb8aa3b, v139
	v_exp_f32_e32 v143, v143
	v_add_f32_e32 v134, 1.0, v134
	v_rcp_f32_e32 v134, v134
	v_add_f32_e32 v143, 1.0, v143
	v_rcp_f32_e32 v143, v143
	v_mov_b32_e32 v135, v134
	v_mov_b32_e32 v139, v143
	v_cvt_pk_bf16_f32 v134, v136, v137
	v_cvt_pk_bf16_f32 v135, v142, v135
	v_cvt_pk_bf16_f32 v136, v140, v141
	v_cvt_pk_bf16_f32 v137, v138, v139
	global_store_dwordx4 v[132:133], v[134:137], off
	v_pk_mul_f32 v[138:139], v[80:81], v[0:1] op_sel_hi:[1,0]
	v_pk_mul_f32 v[140:141], v[78:79], v[0:1] op_sel_hi:[1,0]
	v_pk_mul_f32 v[136:137], v[86:87], v[0:1] op_sel_hi:[1,0]
	v_pk_mul_f32 v[134:135], v[88:89], v[0:1] op_sel_hi:[1,0]
	v_mul_f32_e32 v0, 0xbfb8aa3b, v136
	v_exp_f32_e32 v0, v0
	v_mul_f32_e32 v142, 0xbfb8aa3b, v140
	v_exp_f32_e32 v142, v142
	v_add_f32_e32 v0, 1.0, v0
	v_rcp_f32_e32 v0, v0
	v_add_f32_e32 v142, 1.0, v142
	v_rcp_f32_e32 v142, v142
	v_mul_f32_e32 v140, 0xbfb8aa3b, v137
	v_mov_b32_e32 v136, v142
	v_exp_f32_e32 v140, v140
	v_mul_f32_e32 v142, 0xbfb8aa3b, v141
	v_exp_f32_e32 v142, v142
	v_add_f32_e32 v140, 1.0, v140
	v_rcp_f32_e32 v140, v140
	v_add_f32_e32 v142, 1.0, v142
	v_rcp_f32_e32 v142, v142
	v_mov_b32_e32 v137, v140
	v_mul_f32_e32 v141, 0xbfb8aa3b, v134
	v_mov_b32_e32 v140, v142
	v_exp_f32_e32 v141, v141
	v_mul_f32_e32 v142, 0xbfb8aa3b, v138
	v_exp_f32_e32 v142, v142
	v_add_f32_e32 v141, 1.0, v141
	v_rcp_f32_e32 v141, v141
	v_add_f32_e32 v142, 1.0, v142
	v_rcp_f32_e32 v142, v142
	s_nop 0
	v_mov_b32_e32 v138, v142
	v_mul_f32_e32 v134, 0xbfb8aa3b, v135
	v_exp_f32_e32 v134, v134
	v_mul_f32_e32 v142, 0xbfb8aa3b, v139
	v_exp_f32_e32 v142, v142
	v_add_f32_e32 v134, 1.0, v134
	v_rcp_f32_e32 v134, v134
	v_add_f32_e32 v142, 1.0, v142
	v_rcp_f32_e32 v142, v142
	v_mov_b32_e32 v135, v134
	v_mov_b32_e32 v139, v142
	v_cvt_pk_bf16_f32 v134, v0, v137
	v_cvt_pk_bf16_f32 v135, v141, v135
	v_cvt_pk_bf16_f32 v136, v136, v140
	v_cvt_pk_bf16_f32 v137, v138, v139
	global_store_dwordx4 v[132:133], v[134:137], off offset:64
	s_nop 1
	v_or_b32_e32 v134, 48, v170
	v_ashrrev_i32_e32 v135, 31, v134
	v_lshlrev_b64 v[132:133], 11, v[134:135]
	v_lshlrev_b64 v[134:135], 6, v[134:135]
	v_lshl_add_u64 v[146:147], s[92:93], 0, v[134:135]
	global_load_dwordx4 v[134:137], v[146:147], off offset:32
	global_load_dwordx4 v[138:141], v[146:147], off offset:48
	global_load_dwordx4 v[142:145], v[146:147], off
	s_nop 0
	global_load_dwordx4 v[146:149], v[146:147], off offset:16
	v_lshl_add_u64 v[132:133], v[130:131], 0, v[132:133]
	s_waitcnt vmcnt(2)
	v_pk_add_f32 v[136:137], v[136:137], v[140:141]
	v_pk_add_f32 v[134:135], v[134:135], v[138:139]
	s_waitcnt vmcnt(0)
	v_pk_add_f32 v[144:145], v[144:145], v[148:149]
	v_pk_add_f32 v[142:143], v[142:143], v[146:147]
	v_pk_add_f32 v[136:137], v[144:145], v[136:137]
	v_pk_add_f32 v[134:135], v[142:143], v[134:135]
	s_nop 0
	v_pk_mov_b32 v[138:139], v[134:135], v[136:137] op_sel:[1,0]
	v_mov_b32_e32 v135, v137
	v_pk_add_f32 v[134:135], v[138:139], v[134:135]
	s_nop 0
	v_add_f32_e32 v0, v134, v135
	v_fmamk_f32 v0, v0, 0x3a800000, v211
	v_rsq_f32_e32 v0, v0
	s_nop 0
	v_pk_mul_f32 v[136:137], v[82:83], v[0:1] op_sel_hi:[1,0]
	v_pk_mul_f32 v[140:141], v[74:75], v[0:1] op_sel_hi:[1,0]
	v_mul_f32_e32 v142, 0xbfb8aa3b, v136
	v_exp_f32_e32 v142, v142
	v_mul_f32_e32 v143, 0xbfb8aa3b, v140
	v_exp_f32_e32 v143, v143
	v_pk_mul_f32 v[134:135], v[84:85], v[0:1] op_sel_hi:[1,0]
	v_add_f32_e32 v142, 1.0, v142
	v_rcp_f32_e32 v142, v142
	v_add_f32_e32 v143, 1.0, v143
	v_rcp_f32_e32 v143, v143
	v_pk_mul_f32 v[138:139], v[76:77], v[0:1] op_sel_hi:[1,0]
	v_mov_b32_e32 v136, v142
	v_mul_f32_e32 v142, 0xbfb8aa3b, v137
	v_mov_b32_e32 v140, v143
	v_exp_f32_e32 v142, v142
	v_mul_f32_e32 v143, 0xbfb8aa3b, v141
	v_exp_f32_e32 v143, v143
	v_add_f32_e32 v142, 1.0, v142
	v_rcp_f32_e32 v142, v142
	v_add_f32_e32 v143, 1.0, v143
	v_rcp_f32_e32 v143, v143
	v_mov_b32_e32 v137, v142
	v_mul_f32_e32 v142, 0xbfb8aa3b, v134
	v_mov_b32_e32 v141, v143
	v_exp_f32_e32 v142, v142
	v_mul_f32_e32 v143, 0xbfb8aa3b, v138
	v_exp_f32_e32 v143, v143
	v_add_f32_e32 v142, 1.0, v142
	v_rcp_f32_e32 v142, v142
	v_add_f32_e32 v143, 1.0, v143
	v_rcp_f32_e32 v143, v143
	s_nop 0
	v_mov_b32_e32 v138, v143
	v_mul_f32_e32 v134, 0xbfb8aa3b, v135
	v_exp_f32_e32 v134, v134
	v_mul_f32_e32 v143, 0xbfb8aa3b, v139
	v_exp_f32_e32 v143, v143
	v_add_f32_e32 v134, 1.0, v134
	v_rcp_f32_e32 v134, v134
	v_add_f32_e32 v143, 1.0, v143
	v_rcp_f32_e32 v143, v143
	v_mov_b32_e32 v135, v134
	v_mov_b32_e32 v139, v143
	v_cvt_pk_bf16_f32 v134, v136, v137
	v_cvt_pk_bf16_f32 v135, v142, v135
	v_cvt_pk_bf16_f32 v136, v140, v141
	v_cvt_pk_bf16_f32 v137, v138, v139
	global_store_dwordx4 v[132:133], v[134:137], off
	v_pk_mul_f32 v[138:139], v[68:69], v[0:1] op_sel_hi:[1,0]
	v_pk_mul_f32 v[140:141], v[66:67], v[0:1] op_sel_hi:[1,0]
	v_pk_mul_f32 v[136:137], v[70:71], v[0:1] op_sel_hi:[1,0]
	v_pk_mul_f32 v[134:135], v[72:73], v[0:1] op_sel_hi:[1,0]
	v_mul_f32_e32 v0, 0xbfb8aa3b, v136
	v_exp_f32_e32 v0, v0
	v_mul_f32_e32 v142, 0xbfb8aa3b, v140
	v_exp_f32_e32 v142, v142
	v_add_f32_e32 v0, 1.0, v0
	v_rcp_f32_e32 v0, v0
	v_add_f32_e32 v142, 1.0, v142
	v_rcp_f32_e32 v142, v142
	v_mul_f32_e32 v140, 0xbfb8aa3b, v137
	v_mov_b32_e32 v136, v142
	v_exp_f32_e32 v140, v140
	v_mul_f32_e32 v142, 0xbfb8aa3b, v141
	v_exp_f32_e32 v142, v142
	v_add_f32_e32 v140, 1.0, v140
	v_rcp_f32_e32 v140, v140
	v_add_f32_e32 v142, 1.0, v142
	v_rcp_f32_e32 v142, v142
	v_mov_b32_e32 v137, v140
	v_mul_f32_e32 v141, 0xbfb8aa3b, v134
	v_mov_b32_e32 v140, v142
	v_exp_f32_e32 v141, v141
	v_mul_f32_e32 v142, 0xbfb8aa3b, v138
	v_exp_f32_e32 v142, v142
	v_add_f32_e32 v141, 1.0, v141
	v_rcp_f32_e32 v141, v141
	v_add_f32_e32 v142, 1.0, v142
	v_rcp_f32_e32 v142, v142
	s_nop 0
	v_mov_b32_e32 v138, v142
	v_mul_f32_e32 v134, 0xbfb8aa3b, v135
	v_exp_f32_e32 v134, v134
	v_mul_f32_e32 v142, 0xbfb8aa3b, v139
	v_exp_f32_e32 v142, v142
	v_add_f32_e32 v134, 1.0, v134
	v_rcp_f32_e32 v134, v134
	v_add_f32_e32 v142, 1.0, v142
	v_rcp_f32_e32 v142, v142
	v_mov_b32_e32 v135, v134
	v_mov_b32_e32 v139, v142
	v_cvt_pk_bf16_f32 v134, v0, v137
	v_cvt_pk_bf16_f32 v135, v141, v135
	v_cvt_pk_bf16_f32 v136, v136, v140
	v_cvt_pk_bf16_f32 v137, v138, v139
	global_store_dwordx4 v[132:133], v[134:137], off offset:64
	s_nop 1
	v_add_u32_e32 v134, 0x80, v170
	v_ashrrev_i32_e32 v135, 31, v134
	v_lshlrev_b64 v[132:133], 11, v[134:135]
	v_lshlrev_b64 v[134:135], 6, v[134:135]
	v_lshl_add_u64 v[146:147], s[92:93], 0, v[134:135]
	global_load_dwordx4 v[134:137], v[146:147], off offset:32
	global_load_dwordx4 v[138:141], v[146:147], off offset:48
	global_load_dwordx4 v[142:145], v[146:147], off
	s_nop 0
	global_load_dwordx4 v[146:149], v[146:147], off offset:16
	v_lshl_add_u64 v[132:133], v[130:131], 0, v[132:133]
	s_waitcnt vmcnt(2)
	v_pk_add_f32 v[136:137], v[136:137], v[140:141]
	v_pk_add_f32 v[134:135], v[134:135], v[138:139]
	s_waitcnt vmcnt(0)
	v_pk_add_f32 v[144:145], v[144:145], v[148:149]
	v_pk_add_f32 v[142:143], v[142:143], v[146:147]
	v_pk_add_f32 v[136:137], v[144:145], v[136:137]
	v_pk_add_f32 v[134:135], v[142:143], v[134:135]
	s_nop 0
	v_pk_mov_b32 v[138:139], v[134:135], v[136:137] op_sel:[1,0]
	v_mov_b32_e32 v135, v137
	v_pk_add_f32 v[134:135], v[138:139], v[134:135]
	s_nop 0
	v_add_f32_e32 v0, v134, v135
	v_fmamk_f32 v0, v0, 0x3a800000, v211
	v_rsq_f32_e32 v0, v0
	s_nop 0
	v_pk_mul_f32 v[136:137], v[62:63], v[0:1] op_sel_hi:[1,0]
	v_pk_mul_f32 v[140:141], v[58:59], v[0:1] op_sel_hi:[1,0]
	v_mul_f32_e32 v142, 0xbfb8aa3b, v136
	v_exp_f32_e32 v142, v142
	v_mul_f32_e32 v143, 0xbfb8aa3b, v140
	v_exp_f32_e32 v143, v143
	v_pk_mul_f32 v[134:135], v[64:65], v[0:1] op_sel_hi:[1,0]
	v_add_f32_e32 v142, 1.0, v142
	v_rcp_f32_e32 v142, v142
	v_add_f32_e32 v143, 1.0, v143
	v_rcp_f32_e32 v143, v143
	v_pk_mul_f32 v[138:139], v[60:61], v[0:1] op_sel_hi:[1,0]
	v_mov_b32_e32 v136, v142
	v_mul_f32_e32 v142, 0xbfb8aa3b, v137
	v_mov_b32_e32 v140, v143
	v_exp_f32_e32 v142, v142
	v_mul_f32_e32 v143, 0xbfb8aa3b, v141
	v_exp_f32_e32 v143, v143
	v_add_f32_e32 v142, 1.0, v142
	v_rcp_f32_e32 v142, v142
	v_add_f32_e32 v143, 1.0, v143
	v_rcp_f32_e32 v143, v143
	v_mov_b32_e32 v137, v142
	v_mul_f32_e32 v142, 0xbfb8aa3b, v134
	v_mov_b32_e32 v141, v143
	v_exp_f32_e32 v142, v142
	v_mul_f32_e32 v143, 0xbfb8aa3b, v138
	v_exp_f32_e32 v143, v143
	v_add_f32_e32 v142, 1.0, v142
	v_rcp_f32_e32 v142, v142
	v_add_f32_e32 v143, 1.0, v143
	v_rcp_f32_e32 v143, v143
	s_nop 0
	v_mov_b32_e32 v138, v143
	v_mul_f32_e32 v134, 0xbfb8aa3b, v135
	v_exp_f32_e32 v134, v134
	v_mul_f32_e32 v143, 0xbfb8aa3b, v139
	v_exp_f32_e32 v143, v143
	v_add_f32_e32 v134, 1.0, v134
	v_rcp_f32_e32 v134, v134
	v_add_f32_e32 v143, 1.0, v143
	v_rcp_f32_e32 v143, v143
	v_mov_b32_e32 v135, v134
	v_mov_b32_e32 v139, v143
	v_cvt_pk_bf16_f32 v134, v136, v137
	v_cvt_pk_bf16_f32 v135, v142, v135
	v_cvt_pk_bf16_f32 v136, v140, v141
	v_cvt_pk_bf16_f32 v137, v138, v139
	global_store_dwordx4 v[132:133], v[134:137], off
	v_pk_mul_f32 v[138:139], v[48:49], v[0:1] op_sel_hi:[1,0]
	v_pk_mul_f32 v[140:141], v[46:47], v[0:1] op_sel_hi:[1,0]
	v_pk_mul_f32 v[136:137], v[54:55], v[0:1] op_sel_hi:[1,0]
	v_pk_mul_f32 v[134:135], v[56:57], v[0:1] op_sel_hi:[1,0]
	v_mul_f32_e32 v0, 0xbfb8aa3b, v136
	v_exp_f32_e32 v0, v0
	v_mul_f32_e32 v142, 0xbfb8aa3b, v140
	v_exp_f32_e32 v142, v142
	v_add_f32_e32 v0, 1.0, v0
	v_rcp_f32_e32 v0, v0
	v_add_f32_e32 v142, 1.0, v142
	v_rcp_f32_e32 v142, v142
	v_mul_f32_e32 v140, 0xbfb8aa3b, v137
	v_mov_b32_e32 v136, v142
	v_exp_f32_e32 v140, v140
	v_mul_f32_e32 v142, 0xbfb8aa3b, v141
	v_exp_f32_e32 v142, v142
	v_add_f32_e32 v140, 1.0, v140
	v_rcp_f32_e32 v140, v140
	v_add_f32_e32 v142, 1.0, v142
	v_rcp_f32_e32 v142, v142
	v_mov_b32_e32 v137, v140
	v_mul_f32_e32 v141, 0xbfb8aa3b, v134
	v_mov_b32_e32 v140, v142
	v_exp_f32_e32 v141, v141
	v_mul_f32_e32 v142, 0xbfb8aa3b, v138
	v_exp_f32_e32 v142, v142
	v_add_f32_e32 v141, 1.0, v141
	v_rcp_f32_e32 v141, v141
	v_add_f32_e32 v142, 1.0, v142
	v_rcp_f32_e32 v142, v142
	s_nop 0
	v_mov_b32_e32 v138, v142
	v_mul_f32_e32 v134, 0xbfb8aa3b, v135
	v_exp_f32_e32 v134, v134
	v_mul_f32_e32 v142, 0xbfb8aa3b, v139
	v_exp_f32_e32 v142, v142
	v_add_f32_e32 v134, 1.0, v134
	v_rcp_f32_e32 v134, v134
	v_add_f32_e32 v142, 1.0, v142
	v_rcp_f32_e32 v142, v142
	v_mov_b32_e32 v135, v134
	v_mov_b32_e32 v139, v142
	v_cvt_pk_bf16_f32 v134, v0, v137
	v_cvt_pk_bf16_f32 v135, v141, v135
	v_cvt_pk_bf16_f32 v136, v136, v140
	v_cvt_pk_bf16_f32 v137, v138, v139
	global_store_dwordx4 v[132:133], v[134:137], off offset:64
	s_nop 1
	v_add_u32_e32 v134, 0x90, v170
	v_ashrrev_i32_e32 v135, 31, v134
	v_lshlrev_b64 v[132:133], 11, v[134:135]
	v_lshlrev_b64 v[134:135], 6, v[134:135]
	v_lshl_add_u64 v[146:147], s[92:93], 0, v[134:135]
	global_load_dwordx4 v[134:137], v[146:147], off offset:32
	global_load_dwordx4 v[138:141], v[146:147], off offset:48
	global_load_dwordx4 v[142:145], v[146:147], off
	s_nop 0
	global_load_dwordx4 v[146:149], v[146:147], off offset:16
	v_lshl_add_u64 v[132:133], v[130:131], 0, v[132:133]
	s_waitcnt vmcnt(2)
	v_pk_add_f32 v[136:137], v[136:137], v[140:141]
	v_pk_add_f32 v[134:135], v[134:135], v[138:139]
	s_waitcnt vmcnt(0)
	v_pk_add_f32 v[144:145], v[144:145], v[148:149]
	v_pk_add_f32 v[142:143], v[142:143], v[146:147]
	v_pk_add_f32 v[136:137], v[144:145], v[136:137]
	v_pk_add_f32 v[134:135], v[142:143], v[134:135]
	s_nop 0
	v_pk_mov_b32 v[138:139], v[134:135], v[136:137] op_sel:[1,0]
	v_mov_b32_e32 v135, v137
	v_pk_add_f32 v[134:135], v[138:139], v[134:135]
	s_nop 0
	v_add_f32_e32 v0, v134, v135
	v_fmamk_f32 v0, v0, 0x3a800000, v211
	v_rsq_f32_e32 v0, v0
	s_nop 0
	v_pk_mul_f32 v[136:137], v[50:51], v[0:1] op_sel_hi:[1,0]
	v_pk_mul_f32 v[140:141], v[42:43], v[0:1] op_sel_hi:[1,0]
	v_mul_f32_e32 v142, 0xbfb8aa3b, v136
	v_exp_f32_e32 v142, v142
	v_mul_f32_e32 v143, 0xbfb8aa3b, v140
	v_exp_f32_e32 v143, v143
	v_pk_mul_f32 v[134:135], v[52:53], v[0:1] op_sel_hi:[1,0]
	v_add_f32_e32 v142, 1.0, v142
	v_rcp_f32_e32 v142, v142
	v_add_f32_e32 v143, 1.0, v143
	v_rcp_f32_e32 v143, v143
	v_pk_mul_f32 v[138:139], v[44:45], v[0:1] op_sel_hi:[1,0]
	v_mov_b32_e32 v136, v142
	v_mul_f32_e32 v142, 0xbfb8aa3b, v137
	v_mov_b32_e32 v140, v143
	v_exp_f32_e32 v142, v142
	v_mul_f32_e32 v143, 0xbfb8aa3b, v141
	v_exp_f32_e32 v143, v143
	v_add_f32_e32 v142, 1.0, v142
	v_rcp_f32_e32 v142, v142
	v_add_f32_e32 v143, 1.0, v143
	v_rcp_f32_e32 v143, v143
	v_mov_b32_e32 v137, v142
	v_mul_f32_e32 v142, 0xbfb8aa3b, v134
	v_mov_b32_e32 v141, v143
	v_exp_f32_e32 v142, v142
	v_mul_f32_e32 v143, 0xbfb8aa3b, v138
	v_exp_f32_e32 v143, v143
	v_add_f32_e32 v142, 1.0, v142
	v_rcp_f32_e32 v142, v142
	v_add_f32_e32 v143, 1.0, v143
	v_rcp_f32_e32 v143, v143
	s_nop 0
	v_mov_b32_e32 v138, v143
	v_mul_f32_e32 v134, 0xbfb8aa3b, v135
	v_exp_f32_e32 v134, v134
	v_mul_f32_e32 v143, 0xbfb8aa3b, v139
	v_exp_f32_e32 v143, v143
	v_add_f32_e32 v134, 1.0, v134
	v_rcp_f32_e32 v134, v134
	v_add_f32_e32 v143, 1.0, v143
	v_rcp_f32_e32 v143, v143
	v_mov_b32_e32 v135, v134
	v_mov_b32_e32 v139, v143
	v_cvt_pk_bf16_f32 v134, v136, v137
	v_cvt_pk_bf16_f32 v135, v142, v135
	v_cvt_pk_bf16_f32 v136, v140, v141
	v_cvt_pk_bf16_f32 v137, v138, v139
	global_store_dwordx4 v[132:133], v[134:137], off
	v_pk_mul_f32 v[138:139], v[32:33], v[0:1] op_sel_hi:[1,0]
	v_pk_mul_f32 v[140:141], v[30:31], v[0:1] op_sel_hi:[1,0]
	v_pk_mul_f32 v[136:137], v[38:39], v[0:1] op_sel_hi:[1,0]
	v_pk_mul_f32 v[134:135], v[40:41], v[0:1] op_sel_hi:[1,0]
	v_mul_f32_e32 v0, 0xbfb8aa3b, v136
	v_exp_f32_e32 v0, v0
	v_mul_f32_e32 v142, 0xbfb8aa3b, v140
	v_exp_f32_e32 v142, v142
	v_add_f32_e32 v0, 1.0, v0
	v_rcp_f32_e32 v0, v0
	v_add_f32_e32 v142, 1.0, v142
	v_rcp_f32_e32 v142, v142
	v_mul_f32_e32 v140, 0xbfb8aa3b, v137
	v_mov_b32_e32 v136, v142
	v_exp_f32_e32 v140, v140
	v_mul_f32_e32 v142, 0xbfb8aa3b, v141
	v_exp_f32_e32 v142, v142
	v_add_f32_e32 v140, 1.0, v140
	v_rcp_f32_e32 v140, v140
	v_add_f32_e32 v142, 1.0, v142
	v_rcp_f32_e32 v142, v142
	v_mov_b32_e32 v137, v140
	v_mul_f32_e32 v141, 0xbfb8aa3b, v134
	v_mov_b32_e32 v140, v142
	v_exp_f32_e32 v141, v141
	v_mul_f32_e32 v142, 0xbfb8aa3b, v138
	v_exp_f32_e32 v142, v142
	v_add_f32_e32 v141, 1.0, v141
	v_rcp_f32_e32 v141, v141
	v_add_f32_e32 v142, 1.0, v142
	v_rcp_f32_e32 v142, v142
	s_nop 0
	v_mov_b32_e32 v138, v142
	v_mul_f32_e32 v134, 0xbfb8aa3b, v135
	v_exp_f32_e32 v134, v134
	v_mul_f32_e32 v142, 0xbfb8aa3b, v139
	v_exp_f32_e32 v142, v142
	v_add_f32_e32 v134, 1.0, v134
	v_rcp_f32_e32 v134, v134
	v_add_f32_e32 v142, 1.0, v142
	v_rcp_f32_e32 v142, v142
	v_mov_b32_e32 v135, v134
	v_mov_b32_e32 v139, v142
	v_cvt_pk_bf16_f32 v134, v0, v137
	v_cvt_pk_bf16_f32 v135, v141, v135
	v_cvt_pk_bf16_f32 v136, v136, v140
	v_cvt_pk_bf16_f32 v137, v138, v139
	global_store_dwordx4 v[132:133], v[134:137], off offset:64
	s_nop 1
	v_add_u32_e32 v134, 0xa0, v170
	v_ashrrev_i32_e32 v135, 31, v134
	v_lshlrev_b64 v[132:133], 11, v[134:135]
	v_lshlrev_b64 v[134:135], 6, v[134:135]
	v_lshl_add_u64 v[146:147], s[92:93], 0, v[134:135]
	global_load_dwordx4 v[134:137], v[146:147], off offset:32
	global_load_dwordx4 v[138:141], v[146:147], off offset:48
	global_load_dwordx4 v[142:145], v[146:147], off
	s_nop 0
	global_load_dwordx4 v[146:149], v[146:147], off offset:16
	v_lshl_add_u64 v[132:133], v[130:131], 0, v[132:133]
	s_waitcnt vmcnt(2)
	v_pk_add_f32 v[136:137], v[136:137], v[140:141]
	v_pk_add_f32 v[134:135], v[134:135], v[138:139]
	s_waitcnt vmcnt(0)
	v_pk_add_f32 v[144:145], v[144:145], v[148:149]
	v_pk_add_f32 v[142:143], v[142:143], v[146:147]
	v_pk_add_f32 v[136:137], v[144:145], v[136:137]
	v_pk_add_f32 v[134:135], v[142:143], v[134:135]
	s_nop 0
	v_pk_mov_b32 v[138:139], v[134:135], v[136:137] op_sel:[1,0]
	v_mov_b32_e32 v135, v137
	v_pk_add_f32 v[134:135], v[138:139], v[134:135]
	s_nop 0
	v_add_f32_e32 v0, v134, v135
	v_fmamk_f32 v0, v0, 0x3a800000, v211
	v_rsq_f32_e32 v0, v0
	s_nop 0
	v_pk_mul_f32 v[136:137], v[34:35], v[0:1] op_sel_hi:[1,0]
	v_pk_mul_f32 v[140:141], v[26:27], v[0:1] op_sel_hi:[1,0]
	v_mul_f32_e32 v142, 0xbfb8aa3b, v136
	v_exp_f32_e32 v142, v142
	v_mul_f32_e32 v143, 0xbfb8aa3b, v140
	v_exp_f32_e32 v143, v143
	v_pk_mul_f32 v[134:135], v[36:37], v[0:1] op_sel_hi:[1,0]
	v_add_f32_e32 v142, 1.0, v142
	v_rcp_f32_e32 v142, v142
	v_add_f32_e32 v143, 1.0, v143
	v_rcp_f32_e32 v143, v143
	v_pk_mul_f32 v[138:139], v[28:29], v[0:1] op_sel_hi:[1,0]
	v_mov_b32_e32 v136, v142
	v_mul_f32_e32 v142, 0xbfb8aa3b, v137
	v_mov_b32_e32 v140, v143
	v_exp_f32_e32 v142, v142
	v_mul_f32_e32 v143, 0xbfb8aa3b, v141
	v_exp_f32_e32 v143, v143
	v_add_f32_e32 v142, 1.0, v142
	v_rcp_f32_e32 v142, v142
	v_add_f32_e32 v143, 1.0, v143
	v_rcp_f32_e32 v143, v143
	v_mov_b32_e32 v137, v142
	v_mul_f32_e32 v142, 0xbfb8aa3b, v134
	v_mov_b32_e32 v141, v143
	v_exp_f32_e32 v142, v142
	v_mul_f32_e32 v143, 0xbfb8aa3b, v138
	v_exp_f32_e32 v143, v143
	v_add_f32_e32 v142, 1.0, v142
	v_rcp_f32_e32 v142, v142
	v_add_f32_e32 v143, 1.0, v143
	v_rcp_f32_e32 v143, v143
	s_nop 0
	v_mov_b32_e32 v138, v143
	v_mul_f32_e32 v134, 0xbfb8aa3b, v135
	v_exp_f32_e32 v134, v134
	v_mul_f32_e32 v143, 0xbfb8aa3b, v139
	v_exp_f32_e32 v143, v143
	v_add_f32_e32 v134, 1.0, v134
	v_rcp_f32_e32 v134, v134
	v_add_f32_e32 v143, 1.0, v143
	v_rcp_f32_e32 v143, v143
	v_mov_b32_e32 v135, v134
	v_mov_b32_e32 v139, v143
	v_cvt_pk_bf16_f32 v134, v136, v137
	v_cvt_pk_bf16_f32 v135, v142, v135
	v_cvt_pk_bf16_f32 v136, v140, v141
	v_cvt_pk_bf16_f32 v137, v138, v139
	global_store_dwordx4 v[132:133], v[134:137], off
	v_pk_mul_f32 v[138:139], v[16:17], v[0:1] op_sel_hi:[1,0]
	v_pk_mul_f32 v[140:141], v[14:15], v[0:1] op_sel_hi:[1,0]
	v_pk_mul_f32 v[136:137], v[22:23], v[0:1] op_sel_hi:[1,0]
	v_pk_mul_f32 v[134:135], v[24:25], v[0:1] op_sel_hi:[1,0]
	v_mul_f32_e32 v0, 0xbfb8aa3b, v136
	v_exp_f32_e32 v0, v0
	v_mul_f32_e32 v142, 0xbfb8aa3b, v140
	v_exp_f32_e32 v142, v142
	v_add_f32_e32 v0, 1.0, v0
	v_rcp_f32_e32 v0, v0
	v_add_f32_e32 v142, 1.0, v142
	v_rcp_f32_e32 v142, v142
	v_mul_f32_e32 v140, 0xbfb8aa3b, v137
	v_mov_b32_e32 v136, v142
	v_exp_f32_e32 v140, v140
	v_mul_f32_e32 v142, 0xbfb8aa3b, v141
	v_exp_f32_e32 v142, v142
	v_add_f32_e32 v140, 1.0, v140
	v_rcp_f32_e32 v140, v140
	v_add_f32_e32 v142, 1.0, v142
	v_rcp_f32_e32 v142, v142
	v_mov_b32_e32 v137, v140
	v_mul_f32_e32 v141, 0xbfb8aa3b, v134
	v_mov_b32_e32 v140, v142
	v_exp_f32_e32 v141, v141
	v_mul_f32_e32 v142, 0xbfb8aa3b, v138
	v_exp_f32_e32 v142, v142
	v_add_f32_e32 v141, 1.0, v141
	v_rcp_f32_e32 v141, v141
	v_add_f32_e32 v142, 1.0, v142
	v_rcp_f32_e32 v142, v142
	s_nop 0
	v_mov_b32_e32 v138, v142
	v_mul_f32_e32 v134, 0xbfb8aa3b, v135
	v_exp_f32_e32 v134, v134
	v_mul_f32_e32 v142, 0xbfb8aa3b, v139
	v_exp_f32_e32 v142, v142
	v_add_f32_e32 v134, 1.0, v134
	v_rcp_f32_e32 v134, v134
	v_add_f32_e32 v142, 1.0, v142
	v_rcp_f32_e32 v142, v142
	v_mov_b32_e32 v135, v134
	v_mov_b32_e32 v139, v142
	v_cvt_pk_bf16_f32 v134, v0, v137
	v_cvt_pk_bf16_f32 v135, v141, v135
	v_cvt_pk_bf16_f32 v136, v136, v140
	v_cvt_pk_bf16_f32 v137, v138, v139
	global_store_dwordx4 v[132:133], v[134:137], off offset:64
	v_add_u32_e32 v132, 0xb0, v170
	v_ashrrev_i32_e32 v133, 31, v132
	v_lshlrev_b64 v[134:135], 11, v[132:133]
	v_lshlrev_b64 v[132:133], 6, v[132:133]
	v_lshl_add_u64 v[144:145], s[92:93], 0, v[132:133]
	v_lshl_add_u64 v[130:131], v[130:131], 0, v[134:135]
	global_load_dwordx4 v[132:135], v[144:145], off offset:32
	global_load_dwordx4 v[136:139], v[144:145], off offset:48
	global_load_dwordx4 v[140:143], v[144:145], off
	s_nop 0
	global_load_dwordx4 v[144:147], v[144:145], off offset:16
	s_waitcnt vmcnt(2)
	v_pk_add_f32 v[134:135], v[134:135], v[138:139]
	v_pk_add_f32 v[132:133], v[132:133], v[136:137]
	s_waitcnt vmcnt(0)
	v_pk_add_f32 v[142:143], v[142:143], v[146:147]
	v_pk_add_f32 v[140:141], v[140:141], v[144:145]
	v_pk_add_f32 v[134:135], v[142:143], v[134:135]
	v_pk_add_f32 v[132:133], v[140:141], v[132:133]
	s_nop 0
	v_pk_mov_b32 v[136:137], v[132:133], v[134:135] op_sel:[1,0]
	v_mov_b32_e32 v133, v135
	v_pk_add_f32 v[132:133], v[136:137], v[132:133]
	s_nop 0
	v_add_f32_e32 v0, v132, v133
	v_fmamk_f32 v0, v0, 0x3a800000, v211
	v_rsq_f32_e32 v0, v0
	s_nop 0
	v_pk_mul_f32 v[134:135], v[18:19], v[0:1] op_sel_hi:[1,0]
	v_pk_mul_f32 v[138:139], v[10:11], v[0:1] op_sel_hi:[1,0]
	v_mul_f32_e32 v140, 0xbfb8aa3b, v134
	v_exp_f32_e32 v140, v140
	v_mul_f32_e32 v141, 0xbfb8aa3b, v138
	v_exp_f32_e32 v141, v141
	v_pk_mul_f32 v[132:133], v[20:21], v[0:1] op_sel_hi:[1,0]
	v_add_f32_e32 v140, 1.0, v140
	v_rcp_f32_e32 v140, v140
	v_add_f32_e32 v141, 1.0, v141
	v_rcp_f32_e32 v141, v141
	v_pk_mul_f32 v[136:137], v[12:13], v[0:1] op_sel_hi:[1,0]
	v_mov_b32_e32 v134, v140
	v_mul_f32_e32 v140, 0xbfb8aa3b, v135
	v_mov_b32_e32 v138, v141
	v_exp_f32_e32 v140, v140
	v_mul_f32_e32 v141, 0xbfb8aa3b, v139
	v_exp_f32_e32 v141, v141
	v_add_f32_e32 v140, 1.0, v140
	v_rcp_f32_e32 v140, v140
	v_add_f32_e32 v141, 1.0, v141
	v_rcp_f32_e32 v141, v141
	v_mov_b32_e32 v135, v140
	v_mul_f32_e32 v140, 0xbfb8aa3b, v132
	v_mov_b32_e32 v139, v141
	v_exp_f32_e32 v140, v140
	v_mul_f32_e32 v141, 0xbfb8aa3b, v136
	v_exp_f32_e32 v141, v141
	v_add_f32_e32 v140, 1.0, v140
	v_rcp_f32_e32 v140, v140
	v_add_f32_e32 v141, 1.0, v141
	v_rcp_f32_e32 v141, v141
	s_nop 0
	v_mov_b32_e32 v136, v141
	v_mul_f32_e32 v132, 0xbfb8aa3b, v133
	v_exp_f32_e32 v132, v132
	v_mul_f32_e32 v141, 0xbfb8aa3b, v137
	v_exp_f32_e32 v141, v141
	v_add_f32_e32 v132, 1.0, v132
	v_rcp_f32_e32 v132, v132
	v_add_f32_e32 v141, 1.0, v141
	v_rcp_f32_e32 v141, v141
	v_mov_b32_e32 v133, v132
	v_mov_b32_e32 v137, v141
	v_cvt_pk_bf16_f32 v132, v134, v135
	v_cvt_pk_bf16_f32 v133, v140, v133
	v_cvt_pk_bf16_f32 v134, v138, v139
	v_cvt_pk_bf16_f32 v135, v136, v137
	global_store_dwordx4 v[130:131], v[132:135], off
	v_pk_mul_f32 v[136:137], v[4:5], v[0:1] op_sel_hi:[1,0]
	v_pk_mul_f32 v[138:139], v[2:3], v[0:1] op_sel_hi:[1,0]
	v_pk_mul_f32 v[134:135], v[6:7], v[0:1] op_sel_hi:[1,0]
	v_pk_mul_f32 v[132:133], v[8:9], v[0:1] op_sel_hi:[1,0]
	v_mul_f32_e32 v0, 0xbfb8aa3b, v134
	v_exp_f32_e32 v0, v0
	v_mul_f32_e32 v140, 0xbfb8aa3b, v138
	v_exp_f32_e32 v140, v140
	v_add_f32_e32 v0, 1.0, v0
	v_rcp_f32_e32 v0, v0
	v_add_f32_e32 v140, 1.0, v140
	v_rcp_f32_e32 v140, v140
	v_mul_f32_e32 v138, 0xbfb8aa3b, v135
	v_mov_b32_e32 v134, v140
	v_exp_f32_e32 v138, v138
	v_mul_f32_e32 v140, 0xbfb8aa3b, v139
	v_exp_f32_e32 v140, v140
	v_add_f32_e32 v138, 1.0, v138
	v_rcp_f32_e32 v138, v138
	v_add_f32_e32 v140, 1.0, v140
	v_rcp_f32_e32 v140, v140
	v_mov_b32_e32 v135, v138
	v_mul_f32_e32 v139, 0xbfb8aa3b, v132
	v_mov_b32_e32 v138, v140
	v_exp_f32_e32 v139, v139
	v_mul_f32_e32 v140, 0xbfb8aa3b, v136
	v_exp_f32_e32 v140, v140
	v_add_f32_e32 v139, 1.0, v139
	v_rcp_f32_e32 v139, v139
	v_add_f32_e32 v140, 1.0, v140
	v_rcp_f32_e32 v140, v140
	s_nop 0
	v_mov_b32_e32 v136, v140
	v_mul_f32_e32 v132, 0xbfb8aa3b, v133
	v_exp_f32_e32 v132, v132
	v_mul_f32_e32 v140, 0xbfb8aa3b, v137
	v_exp_f32_e32 v140, v140
	v_add_f32_e32 v132, 1.0, v132
	v_rcp_f32_e32 v132, v132
	v_add_f32_e32 v140, 1.0, v140
	v_rcp_f32_e32 v140, v140
	v_mov_b32_e32 v133, v132
	v_mov_b32_e32 v137, v140
	v_cvt_pk_bf16_f32 v132, v0, v135
	v_cvt_pk_bf16_f32 v133, v139, v133
	v_cvt_pk_bf16_f32 v134, v134, v138
	v_cvt_pk_bf16_f32 v135, v136, v137
	global_store_dwordx4 v[130:131], v[132:135], off offset:64
.Lsig_join:
.LBB0_177:
	s_andn2_b64 vcc, exec, s[42:43]
	s_cbranch_vccnz .LBB0_195
	v_lshl_add_u32 v0, s16, 6, v221
	v_readlane_b32 s8, v255, 35
	v_lshlrev_b64 v[134:135], 2, v[0:1]
	v_readlane_b32 s9, v255, 36
	v_ashrrev_i32_e32 v171, 31, v170
	v_lshlrev_b64 v[142:143], 6, v[170:171]
	v_lshl_add_u64 v[136:137], s[8:9], 0, v[134:135]
	v_readlane_b32 s8, v255, 37
	v_readlane_b32 s9, v255, 38
	v_lshl_add_u64 v[130:131], s[86:87], 0, v[134:135]
	v_lshl_add_u64 v[154:155], s[92:93], 0, v[142:143]
	v_lshl_add_u64 v[134:135], s[8:9], 0, v[134:135]
	global_load_dwordx4 v[130:133], v[130:131], off
	v_or_b32_e32 v176, 16, v170
	global_load_dwordx4 v[138:141], v[136:137], off
	v_ashrrev_i32_e32 v177, 31, v176
	global_load_dwordx4 v[134:137], v[134:135], off
	s_nop 0
	global_load_dwordx4 v[142:145], v[154:155], off offset:32
	global_load_dwordx4 v[146:149], v[154:155], off offset:48
	global_load_dwordx4 v[150:153], v[154:155], off
	s_nop 0
	global_load_dwordx4 v[154:157], v[154:155], off offset:16
	v_or_b32_e32 v200, 32, v170
	v_ashrrev_i32_e32 v201, 31, v200
	v_or_b32_e32 v208, 48, v170
	v_ashrrev_i32_e32 v209, 31, v208
	v_readlane_b32 s8, v255, 27
	v_readlane_b32 s9, v255, 28
	s_waitcnt vmcnt(0)
	v_pk_add_f32 v[144:145], v[144:145], v[148:149]
	v_pk_add_f32 v[142:143], v[142:143], v[146:147]
	v_pk_add_f32 v[152:153], v[152:153], v[156:157]
	v_pk_add_f32 v[150:151], v[150:151], v[154:155]
	v_pk_add_f32 v[144:145], v[152:153], v[144:145]
	v_pk_add_f32 v[142:143], v[150:151], v[142:143]
	s_nop 0
	v_pk_mov_b32 v[146:147], v[142:143], v[144:145] op_sel:[1,0]
	v_mov_b32_e32 v143, v145
	v_pk_add_f32 v[142:143], v[146:147], v[142:143]
	s_nop 0
	v_add_f32_e32 v142, v142, v143
	v_fmamk_f32 v142, v142, 0x3a800000, v211
	v_rsq_f32_e32 v142, v142
	s_nop 0
	v_pk_mul_f32 v[144:145], v[126:127], v[142:143] op_sel_hi:[1,0]
	v_pk_mul_f32 v[148:149], v[122:123], v[142:143] op_sel_hi:[1,0]
	v_pk_mul_f32 v[146:147], v[128:129], v[142:143] op_sel_hi:[1,0]
	v_pk_mul_f32 v[194:195], v[148:149], v[144:145]
	v_pk_mul_f32 v[144:145], v[110:111], v[142:143] op_sel_hi:[1,0]
	v_pk_mul_f32 v[150:151], v[124:125], v[142:143] op_sel_hi:[1,0]
	v_mul_f32_e32 v143, 0xbfb8aa3b, v144
	v_exp_f32_e32 v143, v143
	v_pk_mul_f32 v[192:193], v[150:151], v[146:147]
	v_mov_b32_dpp v172, v194 row_ror:1 row_mask:0xf bank_mask:0xf
	v_mov_b32_dpp v229, v194 row_ror:15 row_mask:0xf bank_mask:0xf
	v_add_f32_e32 v143, 1.0, v143
	v_rcp_f32_e32 v146, v143
	v_pk_mul_f32 v[148:149], v[118:119], v[142:143] op_sel_hi:[1,0]
	v_mul_f32_e32 v143, 0xbfb8aa3b, v145
	v_exp_f32_e32 v143, v143
	v_mov_b32_dpp v173, v195 row_ror:1 row_mask:0xf bank_mask:0xf
	v_mov_b32_dpp v230, v195 row_ror:15 row_mask:0xf bank_mask:0xf
	v_mov_b32_dpp v174, v192 row_ror:1 row_mask:0xf bank_mask:0xf
	v_add_f32_e32 v143, 1.0, v143
	v_rcp_f32_e32 v147, v143
	v_mov_b32_dpp v232, v192 row_ror:15 row_mask:0xf bank_mask:0xf
	v_mov_b32_dpp v175, v193 row_ror:1 row_mask:0xf bank_mask:0xf
	v_mov_b32_dpp v236, v193 row_ror:15 row_mask:0xf bank_mask:0xf
	v_pk_mul_f32 v[144:145], v[144:145], v[146:147]
	s_nop 0
	v_pk_mul_f32 v[196:197], v[148:149], v[144:145]
	v_pk_mul_f32 v[144:145], v[112:113], v[142:143] op_sel_hi:[1,0]
	s_nop 0
	v_mul_f32_e32 v143, 0xbfb8aa3b, v144
	v_mul_f32_e32 v147, 0xbfb8aa3b, v145
	v_exp_f32_e32 v143, v143
	v_exp_f32_e32 v147, v147
	v_add_f32_e32 v143, 1.0, v143
	v_add_f32_e32 v147, 1.0, v147
	v_rcp_f32_e32 v146, v143
	v_rcp_f32_e32 v147, v147
	v_pk_mul_f32 v[142:143], v[120:121], v[142:143] op_sel_hi:[1,0]
	v_pk_mul_f32 v[144:145], v[144:145], v[146:147]
	s_nop 0
	v_pk_mul_f32 v[198:199], v[142:143], v[144:145]
	v_lshlrev_b64 v[142:143], 6, v[176:177]
	v_lshl_add_u64 v[154:155], s[92:93], 0, v[142:143]
	global_load_dwordx4 v[142:145], v[154:155], off offset:32
	global_load_dwordx4 v[146:149], v[154:155], off offset:48
	global_load_dwordx4 v[150:153], v[154:155], off
	s_nop 0
	global_load_dwordx4 v[154:157], v[154:155], off offset:16
	s_waitcnt vmcnt(2)
	v_pk_add_f32 v[144:145], v[144:145], v[148:149]
	v_pk_add_f32 v[142:143], v[142:143], v[146:147]
	s_waitcnt vmcnt(0)
	v_pk_add_f32 v[152:153], v[152:153], v[156:157]
	v_pk_add_f32 v[150:151], v[150:151], v[154:155]
	v_pk_add_f32 v[144:145], v[152:153], v[144:145]
	v_pk_add_f32 v[142:143], v[150:151], v[142:143]
	s_nop 0
	v_pk_mov_b32 v[146:147], v[142:143], v[144:145] op_sel:[1,0]
	v_mov_b32_e32 v143, v145
	v_pk_add_f32 v[142:143], v[146:147], v[142:143]
	s_nop 0
	v_add_f32_e32 v142, v142, v143
	v_fmamk_f32 v142, v142, 0x3a800000, v211
	v_rsq_f32_e32 v190, v142
	s_nop 0
	v_pk_mul_f32 v[142:143], v[114:115], v[190:191] op_sel_hi:[1,0]
	v_pk_mul_f32 v[146:147], v[106:107], v[190:191] op_sel_hi:[1,0]
	v_pk_mul_f32 v[144:145], v[116:117], v[190:191] op_sel_hi:[1,0]
	v_pk_mul_f32 v[188:189], v[146:147], v[142:143]
	v_lshlrev_b64 v[142:143], 6, v[200:201]
	v_pk_mul_f32 v[148:149], v[108:109], v[190:191] op_sel_hi:[1,0]
	v_lshl_add_u64 v[154:155], s[92:93], 0, v[142:143]
	v_pk_mul_f32 v[186:187], v[148:149], v[144:145]
	global_load_dwordx4 v[142:145], v[154:155], off offset:32
	global_load_dwordx4 v[146:149], v[154:155], off offset:48
	global_load_dwordx4 v[150:153], v[154:155], off
	s_nop 0
	global_load_dwordx4 v[154:157], v[154:155], off offset:16
	v_mov_b32_dpp v207, v186 row_ror:1 row_mask:0xf bank_mask:0xf
	v_mov_b32_dpp v191, v188 row_ror:1 row_mask:0xf bank_mask:0xf
	v_mov_b32_dpp v213, v188 row_ror:15 row_mask:0xf bank_mask:0xf
	v_mov_b32_dpp v210, v189 row_ror:1 row_mask:0xf bank_mask:0xf
	v_mov_b32_dpp v226, v189 row_ror:15 row_mask:0xf bank_mask:0xf
	v_mov_b32_dpp v227, v186 row_ror:15 row_mask:0xf bank_mask:0xf
	v_mov_b32_dpp v212, v187 row_ror:1 row_mask:0xf bank_mask:0xf
	v_mov_b32_dpp v228, v187 row_ror:15 row_mask:0xf bank_mask:0xf
	s_waitcnt vmcnt(2)
	v_pk_add_f32 v[144:145], v[144:145], v[148:149]
	v_pk_add_f32 v[142:143], v[142:143], v[146:147]
	s_waitcnt vmcnt(0)
	v_pk_add_f32 v[152:153], v[152:153], v[156:157]
	v_pk_add_f32 v[150:151], v[150:151], v[154:155]
	v_pk_add_f32 v[144:145], v[152:153], v[144:145]
	v_pk_add_f32 v[142:143], v[150:151], v[142:143]
	s_nop 0
	v_pk_mov_b32 v[146:147], v[142:143], v[144:145] op_sel:[1,0]
	v_mov_b32_e32 v143, v145
	v_pk_add_f32 v[142:143], v[146:147], v[142:143]
	s_nop 0
	v_add_f32_e32 v142, v142, v143
	v_fmamk_f32 v142, v142, 0x3a800000, v211
	v_rsq_f32_e32 v206, v142
	s_nop 0
	v_pk_mul_f32 v[142:143], v[98:99], v[206:207] op_sel_hi:[1,0]
	v_pk_mul_f32 v[146:147], v[90:91], v[206:207] op_sel_hi:[1,0]
	v_pk_mul_f32 v[144:145], v[100:101], v[206:207] op_sel_hi:[1,0]
	v_pk_mul_f32 v[204:205], v[146:147], v[142:143]
	v_lshlrev_b64 v[142:143], 6, v[208:209]
	v_pk_mul_f32 v[148:149], v[92:93], v[206:207] op_sel_hi:[1,0]
	v_lshl_add_u64 v[154:155], s[92:93], 0, v[142:143]
	v_pk_mul_f32 v[202:203], v[148:149], v[144:145]
	global_load_dwordx4 v[142:145], v[154:155], off offset:32
	global_load_dwordx4 v[146:149], v[154:155], off offset:48
	global_load_dwordx4 v[150:153], v[154:155], off
	s_nop 0
	global_load_dwordx4 v[154:157], v[154:155], off offset:16
	v_mov_b32_dpp v231, v204 row_ror:1 row_mask:0xf bank_mask:0xf
	v_mov_b32_dpp v237, v204 row_ror:15 row_mask:0xf bank_mask:0xf
	v_mov_b32_dpp v234, v205 row_ror:1 row_mask:0xf bank_mask:0xf
	v_mov_b32_dpp v238, v205 row_ror:15 row_mask:0xf bank_mask:0xf
	v_mov_b32_dpp v233, v202 row_ror:1 row_mask:0xf bank_mask:0xf
	v_mov_b32_dpp v239, v202 row_ror:15 row_mask:0xf bank_mask:0xf
	v_mov_b32_dpp v235, v203 row_ror:1 row_mask:0xf bank_mask:0xf
	v_mov_b32_dpp v240, v203 row_ror:15 row_mask:0xf bank_mask:0xf
	s_waitcnt vmcnt(2)
	v_pk_add_f32 v[144:145], v[144:145], v[148:149]
	v_pk_add_f32 v[142:143], v[142:143], v[146:147]
	s_waitcnt vmcnt(0)
	v_pk_add_f32 v[152:153], v[152:153], v[156:157]
	v_pk_add_f32 v[150:151], v[150:151], v[154:155]
	v_pk_add_f32 v[144:145], v[152:153], v[144:145]
	v_pk_add_f32 v[142:143], v[150:151], v[142:143]
	v_lshlrev_b64 v[152:153], 10, v[170:171]
	v_pk_mov_b32 v[146:147], v[142:143], v[144:145] op_sel:[1,0]
	v_mov_b32_e32 v143, v145
	v_pk_add_f32 v[142:143], v[146:147], v[142:143]
	v_lshl_add_u64 v[152:153], v[152:153], 0, v[0:1]
	v_add_f32_e32 v142, v142, v143
	v_fmamk_f32 v142, v142, 0x3a800000, v211
	v_rsq_f32_e32 v150, v142
	s_nop 0
	v_pk_mul_f32 v[144:145], v[82:83], v[150:151] op_sel_hi:[1,0]
	v_pk_mul_f32 v[142:143], v[84:85], v[150:151] op_sel_hi:[1,0]
	v_pk_mul_f32 v[146:147], v[74:75], v[150:151] op_sel_hi:[1,0]
	v_pk_mul_f32 v[148:149], v[76:77], v[150:151] op_sel_hi:[1,0]
	v_pk_mul_f32 v[144:145], v[146:147], v[144:145]
	v_pk_mul_f32 v[142:143], v[148:149], v[142:143]
	s_nop 0
	v_mov_b32_dpp v241, v144 row_ror:1 row_mask:0xf bank_mask:0xf
	v_mov_b32_dpp v146, v144 row_ror:15 row_mask:0xf bank_mask:0xf
	v_mov_b32_dpp v243, v145 row_ror:1 row_mask:0xf bank_mask:0xf
	v_mov_b32_dpp v147, v145 row_ror:15 row_mask:0xf bank_mask:0xf
	v_mov_b32_dpp v242, v142 row_ror:1 row_mask:0xf bank_mask:0xf
	v_mov_b32_dpp v148, v142 row_ror:15 row_mask:0xf bank_mask:0xf
	v_mov_b32_dpp v244, v143 row_ror:1 row_mask:0xf bank_mask:0xf
	v_mov_b32_dpp v149, v143 row_ror:15 row_mask:0xf bank_mask:0xf
	s_and_saveexec_b64 s[42:43], s[8:9]
	s_cbranch_execz .LBB0_180
	v_pk_mul_f32 v[246:247], v[140:141], v[192:193]
	v_pk_mul_f32 v[248:249], v[138:139], v[194:195]
	v_cndmask_b32_e64 v155, v236, v228, s[4:5]
	v_cndmask_b32_e64 v154, v232, v227, s[4:5]
	v_cndmask_b32_e64 v157, v230, v226, s[4:5]
	v_cndmask_b32_e64 v156, v229, v213, s[4:5]
	v_pk_fma_f32 v[246:247], v[132:133], v[174:175], v[246:247]
	v_pk_fma_f32 v[248:249], v[130:131], v[172:173], v[248:249]
	v_pk_fma_f32 v[154:155], v[136:137], v[154:155], v[246:247]
	v_pk_fma_f32 v[156:157], v[134:135], v[156:157], v[248:249]
	v_pk_mul_f32 v[154:155], v[198:199], v[154:155]
	v_pk_mul_f32 v[156:157], v[196:197], v[156:157]
	s_nop 0
	v_cvt_pk_bf16_f32 v156, v156, v157
	v_cvt_pk_bf16_f32 v157, v154, v155
	v_lshl_add_u64 v[154:155], v[152:153], 1, s[72:73]
	global_store_dwordx2 v[154:155], v[156:157], off
